# NSA step loops: DMA-issue control flow straightened (1 taken branch instead of 4 per issued tile), vmcnt wait decision tree replaced by a steady-state fast path
# speedup vs baseline: 1.0202x; 1.0035x over previous
; #define MFMA(a, b, c) __builtin_amdgcn_mfma_f32_32x32x16_f16((a), (b), (c), 0, 0, 0)
; #define QK_LD(dst, s0) do { dst[0] = *(const f16x8*)(Kst + kbe + 512 * ((s0) >> 1)); dst[1] = *(const f16x8*)(Kst + kbe + 512 * ((s0) >> 1) + 8192); \
;     dst[2] = *(const f16x8*)(Kst + kbo + 512 * ((s0) >> 1)); dst[3] = *(const f16x8*)(Kst + kbo + 512 * ((s0) >> 1) + 8192); } while (0)
; #define QK_LD(dst, s0) do { dst[0] = *(const f16x8*)(Kst + kbe + 512 * ((s0) >> 1)); dst[1] = *(const f16x8*)(Kst + kbe + 512 * ((s0) >> 1) + 8192); \
;     dst[2] = *(const f16x8*)(Kst + kbo + 512 * ((s0) >> 1)); dst[3] = *(const f16x8*)(Kst + kbo + 512 * ((s0) >> 1) + 8192); } while (0)
; #define EXP8(c, b0) do { _Pragma("unroll") for (int j_ = 0; j_ < 8; ++j_) { c[(b0) + j_] = fexp2(c[(b0) + j_] - me); s_ += c[(b0) + j_]; } } while (0)
; DI void qk_exp(f32x16& n0, f32x16& n1, const char* Kst, const f16x8 (&qf)[8], unsigned kbe, unsigned kbo, f32x16& c0, f32x16& c1, float me, float& ps) {
;   const f32x16 zero = {0.f, 0.f, 0.f, 0.f, 0.f, 0.f, 0.f, 0.f, 0.f, 0.f, 0.f, 0.f, 0.f, 0.f, 0.f, 0.f};
;   f16x8 ka[4], kb[4];
;     ...
;   float s_ = 0.f;
;   QK_LD(ka, 0);
;   n0 = MFMA(ka[0], qf[0], zero); n1 = MFMA(ka[1], qf[0], zero); n0 = MFMA(ka[2], qf[1], n0); n1 = MFMA(ka[3], qf[1], n1);
;   QK_LD(kb, 2);
;   EXP8(c0, 0);
;   n0 = MFMA(kb[0], qf[2], n0); n1 = MFMA(kb[1], qf[2], n1); n0 = MFMA(kb[2], qf[3], n0); n1 = MFMA(kb[3], qf[3], n1);
;   QK_LD(ka, 4);
;   EXP8(c0, 8);
;   n0 = MFMA(ka[0], qf[4], n0); n1 = MFMA(ka[1], qf[4], n1); n0 = MFMA(ka[2], qf[5], n0); n1 = MFMA(ka[3], qf[5], n1);
;   QK_LD(kb, 6);
;   EXP8(c1, 0);
;   n0 = MFMA(kb[0], qf[6], n0); n1 = MFMA(kb[1], qf[6], n1); n0 = MFMA(kb[2], qf[7], n0); n1 = MFMA(kb[3], qf[7], n1);
;   EXP8(c1, 8);
;   ps = s_;
;     ...
; }
.LBB0_603:
	s_cmp_ge_i32 s23, s14
	s_cbranch_scc0 .LBB0_605
	s_mul_i32 s5, s7, 0x3000
	s_mul_hi_i32 s4, s7, 0x3000
	s_add_u32 s28, s61, s5
	s_addc_u32 s29, s3, s4
	s_add_u32 s4, s28, s17
	s_addc_u32 s5, s29, 0
	s_add_u32 s28, s28, s18
	s_addc_u32 s29, s29, 0
	s_add_i32 s101, s8, s60
	s_mov_b32 m0, s101
	s_nop 0
	global_load_lds_dwordx4 v206, s[4:5]
	s_add_u32 s98, s4, s86
	s_addc_u32 s99, s5, s87
	s_add_i32 m0, s101, 0x2000
	s_nop 0
	global_load_lds_dwordx4 v206, s[98:99]
	s_add_i32 m0, s101, 0x4000
	s_mov_b64 s[4:5], 0
	global_load_lds_dwordx4 v206, s[28:29]
	s_add_u32 s98, s28, s86
	s_addc_u32 s99, s29, s87
	s_add_i32 m0, s101, 0x6000
	s_nop 0
	global_load_lds_dwordx4 v206, s[98:99]
	s_branch .LBB0_610
.LBB0_602:
	s_mov_b32 s23, s8
	s_and_b32 s8, s27, 0x18000
	s_cmp_gt_i32 s23, 1
	s_mov_b64 s[4:5], -1
	s_cbranch_scc0 .LBB0_608
	s_branch .LBB0_603
.LBB0_611:
	s_mov_b32 s8, s23
	s_branch .LBB0_612
.LBB0_605:
	s_mul_i32 s5, s9, 0x3000
	s_mul_hi_i32 s4, s9, 0x3000
	s_add_u32 s28, s61, s5
	s_addc_u32 s29, s3, s4
	s_add_u32 s4, s28, s19
	s_addc_u32 s5, s29, 0
	s_add_u32 s28, s28, s20
	s_addc_u32 s29, s29, 0
	s_add_i32 s101, s8, s60
	s_mov_b32 m0, s101
	s_nop 0
	global_load_lds_dwordx4 v206, s[4:5]
	s_add_u32 s98, s4, s86
	s_addc_u32 s99, s5, s87
	s_add_i32 m0, s101, 0x2000
	s_nop 0
	global_load_lds_dwordx4 v206, s[98:99]
	s_add_i32 m0, s101, 0x4000
	s_nop 0
	global_load_lds_dwordx4 v206, s[28:29]
	s_add_u32 s98, s28, s86
	s_addc_u32 s99, s29, s87
	s_add_i32 m0, s101, 0x6000
	s_nop 0
	global_load_lds_dwordx4 v206, s[98:99]
	s_branch .LBB0_610
.LBB0_608:
	s_ashr_i32 s29, s26, 31
	s_add_u32 s4, s64, s26
	s_addc_u32 s5, s65, s29
	s_add_u32 s28, s80, s26
	s_addc_u32 s29, s81, s29
	s_add_i32 s101, s8, s60
	s_mov_b32 m0, s101
	s_nop 0
	global_load_lds_dwordx4 v162, s[4:5]
	s_add_u32 s98, s4, s34
	s_addc_u32 s99, s5, s35
	s_add_i32 m0, s101, 0x2000
	s_nop 0
	global_load_lds_dwordx4 v162, s[98:99]
	s_add_i32 m0, s101, 0x4000
	s_nop 0
	global_load_lds_dwordx4 v162, s[28:29]
	s_add_u32 s98, s28, s34
	s_addc_u32 s99, s29, s35
	s_add_i32 m0, s101, 0x6000
	s_nop 0
	global_load_lds_dwordx4 v162, s[98:99]
.LBB0_610:
	s_add_i32 s8, s23, 1
	s_cmp_lt_i32 s23, s6
	s_cselect_b64 s[4:5], -1, 0
	s_cmp_lt_i32 s8, s12
	s_cselect_b64 s[28:29], -1, 0
	s_and_b64 s[4:5], s[4:5], s[28:29]
	s_sub_i32 s7, s7, 64
	s_sub_i32 s9, s9, 64
	s_addk_i32 s26, 0x4000
	s_add_i32 s27, s27, 0x8000
	s_and_b64 vcc, exec, s[4:5]
	s_cbranch_vccnz .LBB0_602
.LBB0_612:
	v_cndmask_b32_e64 v204, v233, v194, s[0:1]
	s_lshl_b32 s0, s25, 15
	s_and_b32 s7, s0, 0x18000
	s_waitcnt lgkmcnt(0)
	v_mfma_f32_32x32x16_f16 v[114:129], v[98:101], v[150:153], 0
	v_sub_f32_e32 v82, v82, v204
	v_exp_f32_e32 v217, v82
	v_sub_f32_e32 v83, v83, v204
	v_exp_f32_e32 v218, v83
	v_sub_f32_e32 v83, v84, v204
	v_exp_f32_e32 v219, v83
	v_sub_f32_e32 v83, v85, v204
	v_mfma_f32_32x32x16_f16 v[98:113], v[102:105], v[150:153], 0
	v_exp_f32_e32 v220, v83
	v_sub_f32_e32 v83, v86, v204
	v_add_f32_e32 v82, 0, v217
	v_exp_f32_e32 v221, v83
	v_sub_f32_e32 v83, v87, v204
	v_add_f32_e32 v82, v218, v82
	v_exp_f32_e32 v224, v83
	v_mfma_f32_32x32x16_f16 v[114:129], v[196:199], v[158:161], v[114:129]
	v_sub_f32_e32 v83, v88, v204
	v_add_f32_e32 v82, v219, v82
	v_exp_f32_e32 v225, v83
	v_sub_f32_e32 v83, v89, v204
	v_add_f32_e32 v82, v220, v82
	v_exp_f32_e32 v226, v83
	v_add_f32_e32 v82, v221, v82
	v_mfma_f32_32x32x16_f16 v[98:113], v[200:203], v[158:161], v[98:113]
	ds_read_b128 v[196:199], v205 offset:512
	ds_read_b128 v[200:203], v205 offset:8704
	ds_read_b128 v[208:211], v216 offset:512
	ds_read_b128 v[212:215], v216 offset:8704
	v_add_f32_e32 v82, v224, v82
	v_add_f32_e32 v82, v225, v82
	v_add_f32_e32 v227, v226, v82
	v_sub_f32_e32 v90, v90, v204
	v_sub_f32_e32 v91, v91, v204
	v_sub_f32_e32 v66, v66, v204
	s_waitcnt lgkmcnt(0)
	v_mfma_f32_32x32x16_f16 v[114:129], v[196:199], v[142:145], v[114:129]
	v_sub_f32_e32 v67, v67, v204
	s_lshl_b32 s0, s22, 15
	s_and_b32 s9, s0, 0x10000
	v_mfma_f32_32x32x16_f16 v[98:113], v[200:203], v[142:145], v[98:113]
	ds_read_b128 v[82:85], v205 offset:1024
	ds_read_b128 v[86:89], v205 offset:9216
	ds_read_b128 v[196:199], v216 offset:1024
	ds_read_b128 v[200:203], v216 offset:9216
	v_mfma_f32_32x32x16_f16 v[114:129], v[208:211], v[154:157], v[114:129]
	v_exp_f32_e32 v208, v90
	v_exp_f32_e32 v209, v91
	v_sub_f32_e32 v91, v92, v204
	v_exp_f32_e32 v210, v91
	v_sub_f32_e32 v91, v93, v204
	v_exp_f32_e32 v211, v91
	v_sub_f32_e32 v91, v94, v204
	v_mfma_f32_32x32x16_f16 v[98:113], v[212:215], v[154:157], v[98:113]
	v_add_f32_e32 v90, v208, v227
	v_exp_f32_e32 v212, v91
	v_sub_f32_e32 v91, v95, v204
	v_add_f32_e32 v90, v209, v90
	v_exp_f32_e32 v213, v91
	v_sub_f32_e32 v91, v96, v204
	v_add_f32_e32 v90, v210, v90
	s_waitcnt lgkmcnt(0)
	v_mfma_f32_32x32x16_f16 v[114:129], v[82:85], v[138:141], v[114:129]
	v_exp_f32_e32 v214, v91
	v_sub_f32_e32 v91, v97, v204
	v_add_f32_e32 v90, v211, v90
	v_exp_f32_e32 v215, v91
	v_add_f32_e32 v90, v212, v90
	v_add_f32_e32 v90, v213, v90
	v_add_f32_e32 v90, v214, v90
	v_mfma_f32_32x32x16_f16 v[98:113], v[86:89], v[138:141], v[98:113]
	v_add_f32_e32 v227, v215, v90
	ds_read_b128 v[82:85], v205 offset:1536
	ds_read_b128 v[86:89], v205 offset:9728
	ds_read_b128 v[90:93], v216 offset:1536
	ds_read_b128 v[94:97], v216 offset:9728
	v_add_u32_e32 v205, s9, v192
	v_mfma_f32_32x32x16_f16 v[114:129], v[196:199], v[146:149], v[114:129]
	v_exp_f32_e32 v196, v66
	v_exp_f32_e32 v197, v67
	v_sub_f32_e32 v67, v68, v204
	v_exp_f32_e32 v198, v67
	v_sub_f32_e32 v67, v69, v204
	v_exp_f32_e32 v199, v67
	v_sub_f32_e32 v67, v70, v204
	v_mfma_f32_32x32x16_f16 v[98:113], v[200:203], v[146:149], v[98:113]
	v_add_f32_e32 v66, v196, v227
	v_exp_f32_e32 v200, v67
	v_sub_f32_e32 v67, v71, v204
	v_add_f32_e32 v66, v197, v66
	v_exp_f32_e32 v201, v67
	v_sub_f32_e32 v67, v72, v204
	v_add_f32_e32 v66, v198, v66
	s_waitcnt lgkmcnt(0)
; #define SBAR() __builtin_amdgcn_sched_barrier(0)
; DI void pv_max(f32x16 (&o)[4], unsigned vb0, unsigned vb1, const f32x16& p0, const f32x16& p1, const f32x16& n0, const f32x16& n1, float& pm) {
;   f16x8 pb[4]; pb[0] = pack8(p0, 0); pb[1] = pack8(p0, 1); pb[2] = pack8(p1, 0); pb[3] = pack8(p1, 1);
;   VFrag fa;
;   float mx = n0[0];
;   pv_rd<0>(fa, vb0, vb1);
;   asm volatile("s_waitcnt lgkmcnt(0)" ::: "memory"); SBAR();
;   pv_mm(o[0], fa, pb);
;   pv_rd<1>(fa, vb0, vb1);
; #pragma unroll
;   for (int r = 1; r < 8; ++r) mx = fmaxf(mx, n0[r]);
;   asm volatile("s_waitcnt lgkmcnt(0)" ::: "memory"); SBAR();
;   pv_mm(o[1], fa, pb);
;   pv_rd<2>(fa, vb0, vb1);
; #pragma unroll
;   for (int r = 8; r < 16; ++r) mx = fmaxf(mx, n0[r]);
;   asm volatile("s_waitcnt lgkmcnt(0)" ::: "memory"); SBAR();
;   pv_mm(o[2], fa, pb);
;   pv_rd<3>(fa, vb0, vb1);
; #pragma unroll
;   for (int r = 0; r < 8; ++r) mx = fmaxf(mx, n1[r]);
;   asm volatile("s_waitcnt lgkmcnt(0)" ::: "memory"); SBAR();
;   pv_mm(o[3], fa, pb);
; #pragma unroll
;   for (int r = 8; r < 16; ++r) mx = fmaxf(mx, n1[r]);
;   pm = mx;
; }
	v_mfma_f32_32x32x16_f16 v[114:129], v[82:85], v[130:133], v[114:129]
	v_exp_f32_e32 v202, v67
	v_sub_f32_e32 v67, v73, v204
	v_add_f32_e32 v66, v199, v66
	v_exp_f32_e32 v203, v67
	v_sub_f32_e32 v67, v74, v204
	v_add_f32_e32 v66, v200, v66
	v_add_f32_e32 v66, v201, v66
	v_mfma_f32_32x32x16_f16 v[98:113], v[86:89], v[130:133], v[98:113]
	v_exp_f32_e32 v86, v67
	v_sub_f32_e32 v67, v75, v204
	v_exp_f32_e32 v87, v67
	v_sub_f32_e32 v67, v76, v204
	v_add_f32_e32 v66, v202, v66
	v_exp_f32_e32 v88, v67
	v_sub_f32_e32 v67, v77, v204
	v_add_f32_e32 v66, v203, v66
	v_exp_f32_e32 v89, v67
	v_sub_f32_e32 v67, v78, v204
	v_mfma_f32_32x32x16_f16 v[114:129], v[90:93], v[134:137], v[114:129]
	v_add_f32_e32 v66, v86, v66
	v_exp_f32_e32 v90, v67
	v_sub_f32_e32 v67, v79, v204
	v_add_f32_e32 v66, v87, v66
	v_exp_f32_e32 v91, v67
	v_sub_f32_e32 v67, v80, v204
	v_add_f32_e32 v66, v88, v66
	v_exp_f32_e32 v92, v67
	v_sub_f32_e32 v67, v81, v204
	v_add_f32_e32 v66, v89, v66
	v_exp_f32_e32 v93, v67
	v_add_f32_e32 v66, v90, v66
	v_add_f32_e32 v66, v91, v66
	v_add_f32_e32 v66, v92, v66
	v_add_f32_e32 v66, v93, v66
	v_add_f32_e32 v195, v195, v66
	v_add_u32_e32 v204, s9, v1
	ds_read_b64_tr_b16 v[66:67], v204 offset:0
	ds_read_b64_tr_b16 v[68:69], v205 offset:0x800
	ds_read_b64_tr_b16 v[70:71], v204 offset:0x1000
	v_mfma_f32_32x32x16_f16 v[98:113], v[94:97], v[134:137], v[98:113]
	ds_read_b64_tr_b16 v[72:73], v205 offset:0x1800
	ds_read_b64_tr_b16 v[74:75], v204 offset:0x2000
	ds_read_b64_tr_b16 v[76:77], v205 offset:0x2800
	ds_read_b64_tr_b16 v[78:79], v204 offset:0x3000
	ds_read_b64_tr_b16 v[80:81], v205 offset:0x3800
	s_waitcnt lgkmcnt(0)
	v_cvt_pk_f16_f32 v85, v225, v226
	v_cvt_pk_f16_f32 v84, v221, v224
	v_cvt_pk_f16_f32 v83, v219, v220
	v_cvt_pk_f16_f32 v82, v217, v218
	s_nop 1
	v_mfma_f32_32x32x16_f16 v[50:65], v[66:69], v[82:85], v[50:65]
	v_cvt_pk_f16_f32 v69, v214, v215
	v_cvt_pk_f16_f32 v68, v212, v213
	v_cvt_pk_f16_f32 v67, v210, v211
	v_cvt_pk_f16_f32 v66, v208, v209
	s_nop 1
	v_mfma_f32_32x32x16_f16 v[50:65], v[70:73], v[66:69], v[50:65]
	v_cvt_pk_f16_f32 v73, v202, v203
	v_cvt_pk_f16_f32 v72, v200, v201
	v_cvt_pk_f16_f32 v71, v198, v199
	v_cvt_pk_f16_f32 v70, v196, v197
	v_max_f32_e32 v196, v115, v115
	v_max_f32_e32 v197, v114, v114
	v_max_f32_e32 v196, v197, v196
	v_mfma_f32_32x32x16_f16 v[50:65], v[74:77], v[70:73], v[50:65]
	v_cvt_pk_f16_f32 v77, v92, v93
	v_cvt_pk_f16_f32 v76, v90, v91
	v_cvt_pk_f16_f32 v75, v88, v89
	v_cvt_pk_f16_f32 v74, v86, v87
	v_max3_f32 v196, v196, v116, v117
	v_max3_f32 v196, v196, v118, v119
	v_max3_f32 v196, v196, v120, v121
	v_mfma_f32_32x32x16_f16 v[50:65], v[78:81], v[74:77], v[50:65]
	ds_read_b64_tr_b16 v[78:79], v204 offset:0x200
	ds_read_b64_tr_b16 v[80:81], v205 offset:0xa00
	ds_read_b64_tr_b16 v[86:87], v204 offset:0x1200
	ds_read_b64_tr_b16 v[88:89], v205 offset:0x1a00
	ds_read_b64_tr_b16 v[90:91], v204 offset:0x2200
	ds_read_b64_tr_b16 v[92:93], v205 offset:0x2a00
	ds_read_b64_tr_b16 v[94:95], v204 offset:0x3200
	ds_read_b64_tr_b16 v[96:97], v205 offset:0x3a00
	s_waitcnt lgkmcnt(0)
	s_nop 0
	v_mfma_f32_32x32x16_f16 v[34:49], v[78:81], v[82:85], v[34:49]
	ds_read_b64_tr_b16 v[78:79], v204 offset:0x400
	ds_read_b64_tr_b16 v[80:81], v205 offset:0xc00
	v_max3_f32 v196, v196, v122, v123
	v_max3_f32 v196, v196, v124, v125
	v_max3_f32 v196, v196, v126, v127
	v_max3_f32 v196, v196, v128, v129
	v_mfma_f32_32x32x16_f16 v[34:49], v[86:89], v[66:69], v[34:49]
	ds_read_b64_tr_b16 v[86:87], v204 offset:0x1400
	ds_read_b64_tr_b16 v[88:89], v205 offset:0x1c00
	v_mfma_f32_32x32x16_f16 v[34:49], v[90:93], v[70:73], v[34:49]
	ds_read_b64_tr_b16 v[90:91], v204 offset:0x2400
	ds_read_b64_tr_b16 v[92:93], v205 offset:0x2c00
	v_mfma_f32_32x32x16_f16 v[34:49], v[94:97], v[74:77], v[34:49]
	ds_read_b64_tr_b16 v[94:95], v204 offset:0x3400
	ds_read_b64_tr_b16 v[96:97], v205 offset:0x3c00
	s_waitcnt lgkmcnt(0)
	v_mfma_f32_32x32x16_f16 v[18:33], v[78:81], v[82:85], v[18:33]
	ds_read_b64_tr_b16 v[78:79], v204 offset:0x600
	ds_read_b64_tr_b16 v[80:81], v205 offset:0xe00
	v_max3_f32 v196, v196, v98, v99
	v_max3_f32 v196, v196, v100, v101
	v_max3_f32 v196, v196, v102, v103
	v_max3_f32 v196, v196, v104, v105
	v_mfma_f32_32x32x16_f16 v[18:33], v[86:89], v[66:69], v[18:33]
	ds_read_b64_tr_b16 v[86:87], v204 offset:0x1600
	ds_read_b64_tr_b16 v[88:89], v205 offset:0x1e00
	v_mfma_f32_32x32x16_f16 v[18:33], v[90:93], v[70:73], v[18:33]
	ds_read_b64_tr_b16 v[90:91], v204 offset:0x2600
	ds_read_b64_tr_b16 v[92:93], v205 offset:0x2e00
	v_mfma_f32_32x32x16_f16 v[18:33], v[94:97], v[74:77], v[18:33]
	ds_read_b64_tr_b16 v[94:95], v204 offset:0x3600
	ds_read_b64_tr_b16 v[96:97], v205 offset:0x3e00
	s_waitcnt lgkmcnt(0)
	v_mfma_f32_32x32x16_f16 v[2:17], v[78:81], v[82:85], v[2:17]
	v_max3_f32 v78, v196, v106, v107
	v_max3_f32 v78, v78, v108, v109
	s_add_i32 s0, s24, s16
	v_mfma_f32_32x32x16_f16 v[2:17], v[86:89], v[66:69], v[2:17]
	v_max3_f32 v66, v78, v110, v111
	v_max3_f32 v66, v66, v112, v113
	v_mov_b32_e32 v68, v66
	s_nop 1
	v_permlane32_swap_b32_e32 v66, v68
	v_bfe_u32 v67, v193, s0, 1
	v_max_f32_e32 v68, v68, v68
	v_mfma_f32_32x32x16_f16 v[2:17], v[90:93], v[70:73], v[2:17]
	v_max_f32_e32 v66, v66, v66
	v_max_f32_e32 v66, v66, v68
	v_cmp_eq_u32_e64 s[0:1], 0, v67
	s_nop 1
	v_cndmask_b32_e64 v66, v66, v232, s[0:1]
	v_sub_f32_e32 v67, v66, v194
	v_mfma_f32_32x32x16_f16 v[2:17], v[94:97], v[74:77], v[2:17]
	v_cmp_ge_f32_e32 vcc, s73, v67
	s_cmp_eq_u64 vcc, exec
	s_cbranch_scc1 .LBB0_614
; DI float fexp2(float x) { return __builtin_amdgcn_exp2f(x); }
; #define VWAIT(n) asm volatile("s_waitcnt vmcnt(" #n ")" ::: "memory")
; DI void osm_decide(float pmn, float& m, float& l, f32x16 (&o)[4]) {
;   if (!__all(pmn - m <= THR)) {
;     float mn = fmaxf(m, pmn); float alpha = fexp2(m - mn); m = mn; l *= alpha;
; #pragma unroll
;     for (int d = 0; d < 4; ++d)
; #pragma unroll
;       for (int r = 0; r < 16; ++r) o[d][r] *= alpha;
;   }
; }
; DI void ring_wait4(int rem) {
;   if (rem >= 3) VWAIT(12); else if (rem == 2) VWAIT(8); else if (rem == 1) VWAIT(4); else VWAIT(0);
; }
	v_max_f32_e32 v66, v66, v66
	v_max_f32_e32 v67, v194, v194
	v_max_f32_e32 v67, v67, v66
	v_sub_f32_e32 v66, v194, v67
	v_exp_f32_e32 v66, v66
	v_mov_b32_e32 v194, v67
	v_mul_f32_e32 v195, v195, v66
	v_pk_mul_f32 v[64:65], v[64:65], v[66:67] op_sel_hi:[1,0]
	v_pk_mul_f32 v[62:63], v[62:63], v[66:67] op_sel_hi:[1,0]
	v_pk_mul_f32 v[60:61], v[60:61], v[66:67] op_sel_hi:[1,0]
	v_pk_mul_f32 v[58:59], v[58:59], v[66:67] op_sel_hi:[1,0]
	v_pk_mul_f32 v[56:57], v[56:57], v[66:67] op_sel_hi:[1,0]
	v_pk_mul_f32 v[54:55], v[54:55], v[66:67] op_sel_hi:[1,0]
	v_pk_mul_f32 v[52:53], v[52:53], v[66:67] op_sel_hi:[1,0]
	v_pk_mul_f32 v[50:51], v[50:51], v[66:67] op_sel_hi:[1,0]
	v_pk_mul_f32 v[48:49], v[48:49], v[66:67] op_sel_hi:[1,0]
	v_pk_mul_f32 v[46:47], v[46:47], v[66:67] op_sel_hi:[1,0]
	v_pk_mul_f32 v[44:45], v[44:45], v[66:67] op_sel_hi:[1,0]
	v_pk_mul_f32 v[42:43], v[42:43], v[66:67] op_sel_hi:[1,0]
	v_pk_mul_f32 v[40:41], v[40:41], v[66:67] op_sel_hi:[1,0]
	v_pk_mul_f32 v[38:39], v[38:39], v[66:67] op_sel_hi:[1,0]
	v_pk_mul_f32 v[36:37], v[36:37], v[66:67] op_sel_hi:[1,0]
	v_pk_mul_f32 v[34:35], v[34:35], v[66:67] op_sel_hi:[1,0]
	v_pk_mul_f32 v[32:33], v[32:33], v[66:67] op_sel_hi:[1,0]
	v_pk_mul_f32 v[30:31], v[30:31], v[66:67] op_sel_hi:[1,0]
	v_pk_mul_f32 v[28:29], v[28:29], v[66:67] op_sel_hi:[1,0]
	v_pk_mul_f32 v[26:27], v[26:27], v[66:67] op_sel_hi:[1,0]
	v_pk_mul_f32 v[24:25], v[24:25], v[66:67] op_sel_hi:[1,0]
	v_pk_mul_f32 v[22:23], v[22:23], v[66:67] op_sel_hi:[1,0]
	v_pk_mul_f32 v[20:21], v[20:21], v[66:67] op_sel_hi:[1,0]
	v_pk_mul_f32 v[18:19], v[18:19], v[66:67] op_sel_hi:[1,0]
	v_pk_mul_f32 v[16:17], v[16:17], v[66:67] op_sel_hi:[1,0]
	v_pk_mul_f32 v[14:15], v[14:15], v[66:67] op_sel_hi:[1,0]
	v_pk_mul_f32 v[12:13], v[12:13], v[66:67] op_sel_hi:[1,0]
	v_pk_mul_f32 v[10:11], v[10:11], v[66:67] op_sel_hi:[1,0]
	v_pk_mul_f32 v[8:9], v[8:9], v[66:67] op_sel_hi:[1,0]
	v_pk_mul_f32 v[6:7], v[6:7], v[66:67] op_sel_hi:[1,0]
	v_pk_mul_f32 v[4:5], v[4:5], v[66:67] op_sel_hi:[1,0]
	v_pk_mul_f32 v[2:3], v[2:3], v[66:67] op_sel_hi:[1,0]
.LBB0_614:
	s_sub_i32 s23, s8, s22
	s_cmp_lg_u32 s23, 4
	s_cbranch_scc1 .Lvm_slow0
	s_waitcnt vmcnt(4)

; #define VWAIT(n) asm volatile("s_waitcnt vmcnt(" #n ")" ::: "memory")
; DI void ring_wait4(int rem) {
;   if (rem >= 3) VWAIT(12); else if (rem == 2) VWAIT(8); else if (rem == 1) VWAIT(4); else VWAIT(0);
; }
.LBB0_628:
	s_cmp_ge_i32 s8, s14
	s_cbranch_scc0 .LBB0_630
	s_mul_i32 s5, s25, 0x3000
	s_mul_hi_i32 s4, s25, 0x3000
	s_add_u32 s29, s61, s5
	s_addc_u32 s40, s3, s4
	s_add_u32 s4, s29, s17
	s_addc_u32 s5, s40, 0
	s_add_u32 s42, s29, s18
	s_addc_u32 s43, s40, 0
	s_add_i32 s101, s23, s60
	s_mov_b32 m0, s101
	s_nop 0
	global_load_lds_dwordx4 v206, s[4:5]
	s_add_u32 s98, s4, s86
	s_addc_u32 s99, s5, s87
	s_add_i32 m0, s101, 0x2000
	s_nop 0
	global_load_lds_dwordx4 v206, s[98:99]
	s_add_i32 m0, s101, 0x4000
	s_mov_b64 s[4:5], 0
	global_load_lds_dwordx4 v206, s[42:43]
	s_add_u32 s98, s42, s86
	s_addc_u32 s99, s43, s87
	s_add_i32 m0, s101, 0x6000
	s_nop 0
	global_load_lds_dwordx4 v206, s[98:99]
	s_branch .LBB0_635
.Lvm_slow0:
	s_add_i32 s4, s23, -3
	s_cmp_lt_i32 s4, 3
	s_mov_b64 s[4:5], -1
	s_cbranch_scc0 .LBB0_623
	s_cmp_gt_i32 s23, 4
	s_cbranch_scc0 .LBB0_617
	s_waitcnt vmcnt(8)
	s_mov_b64 s[4:5], 0

; #define MFMA(a, b, c) __builtin_amdgcn_mfma_f32_32x32x16_f16((a), (b), (c), 0, 0, 0)
; #define QK_LD(dst, s0) do { dst[0] = *(const f16x8*)(Kst + kbe + 512 * ((s0) >> 1)); dst[1] = *(const f16x8*)(Kst + kbe + 512 * ((s0) >> 1) + 8192); \
;     dst[2] = *(const f16x8*)(Kst + kbo + 512 * ((s0) >> 1)); dst[3] = *(const f16x8*)(Kst + kbo + 512 * ((s0) >> 1) + 8192); } while (0)
; #define QK_LD(dst, s0) do { dst[0] = *(const f16x8*)(Kst + kbe + 512 * ((s0) >> 1)); dst[1] = *(const f16x8*)(Kst + kbe + 512 * ((s0) >> 1) + 8192); \
;     dst[2] = *(const f16x8*)(Kst + kbo + 512 * ((s0) >> 1)); dst[3] = *(const f16x8*)(Kst + kbo + 512 * ((s0) >> 1) + 8192); } while (0)
; #define EXP8(c, b0) do { _Pragma("unroll") for (int j_ = 0; j_ < 8; ++j_) { c[(b0) + j_] = fexp2(c[(b0) + j_] - me); s_ += c[(b0) + j_]; } } while (0)
; #define VWAIT(n) asm volatile("s_waitcnt vmcnt(" #n ")" ::: "memory")
; DI void qk_exp(f32x16& n0, f32x16& n1, const char* Kst, const f16x8 (&qf)[8], unsigned kbe, unsigned kbo, f32x16& c0, f32x16& c1, float me, float& ps) {
;   const f32x16 zero = {0.f, 0.f, 0.f, 0.f, 0.f, 0.f, 0.f, 0.f, 0.f, 0.f, 0.f, 0.f, 0.f, 0.f, 0.f, 0.f};
;   f16x8 ka[4], kb[4];
;     ...
;   float s_ = 0.f;
;   QK_LD(ka, 0);
;   n0 = MFMA(ka[0], qf[0], zero); n1 = MFMA(ka[1], qf[0], zero); n0 = MFMA(ka[2], qf[1], n0); n1 = MFMA(ka[3], qf[1], n1);
;   QK_LD(kb, 2);
;   EXP8(c0, 0);
;   n0 = MFMA(kb[0], qf[2], n0); n1 = MFMA(kb[1], qf[2], n1); n0 = MFMA(kb[2], qf[3], n0); n1 = MFMA(kb[3], qf[3], n1);
;   QK_LD(ka, 4);
;   EXP8(c0, 8);
;   n0 = MFMA(ka[0], qf[4], n0); n1 = MFMA(ka[1], qf[4], n1); n0 = MFMA(ka[2], qf[5], n0); n1 = MFMA(ka[3], qf[5], n1);
;   QK_LD(kb, 6);
;   EXP8(c1, 0);
;   n0 = MFMA(kb[0], qf[6], n0); n1 = MFMA(kb[1], qf[6], n1); n0 = MFMA(kb[2], qf[7], n0); n1 = MFMA(kb[3], qf[7], n1);
;   EXP8(c1, 8);
;   ps = s_;
;     ...
; }
; DI void ring_wait4(int rem) {
;   if (rem >= 3) VWAIT(12); else if (rem == 2) VWAIT(8); else if (rem == 1) VWAIT(4); else VWAIT(0);
; }
.LBB0_623:
	s_and_b64 vcc, exec, s[4:5]
	s_cbranch_vccz .LBB0_625
	s_waitcnt vmcnt(12)
	s_branch .LBB0_625
.LBB0_627:
	s_mov_b32 s8, s23
	s_and_b32 s23, s28, 0x18000
	s_cmp_gt_i32 s8, 1
	s_mov_b64 s[4:5], -1
	s_cbranch_scc0 .LBB0_633
	s_branch .LBB0_628
.LBB0_636:
	s_mov_b32 s23, s8
	s_branch .LBB0_637
.LBB0_630:
	s_mul_i32 s5, s26, 0x3000
	s_mul_hi_i32 s4, s26, 0x3000
	s_add_u32 s29, s61, s5
	s_addc_u32 s40, s3, s4
	s_add_u32 s4, s29, s19
	s_addc_u32 s5, s40, 0
	s_add_u32 s42, s29, s20
	s_addc_u32 s43, s40, 0
	s_add_i32 s101, s23, s60
	s_mov_b32 m0, s101
	s_nop 0
	global_load_lds_dwordx4 v206, s[4:5]
	s_add_u32 s98, s4, s86
	s_addc_u32 s99, s5, s87
	s_add_i32 m0, s101, 0x2000
	s_nop 0
	global_load_lds_dwordx4 v206, s[98:99]
	s_add_i32 m0, s101, 0x4000
	s_nop 0
	global_load_lds_dwordx4 v206, s[42:43]
	s_add_u32 s98, s42, s86
	s_addc_u32 s99, s43, s87
	s_add_i32 m0, s101, 0x6000
	s_nop 0
	global_load_lds_dwordx4 v206, s[98:99]
	s_branch .LBB0_635
.LBB0_633:
	s_ashr_i32 s29, s27, 31
	s_add_u32 s4, s64, s27
	s_addc_u32 s5, s65, s29
	s_add_u32 s42, s80, s27
	s_addc_u32 s43, s81, s29
	s_add_i32 s101, s23, s60
	s_mov_b32 m0, s101
	s_nop 0
	global_load_lds_dwordx4 v162, s[4:5]
	s_add_u32 s98, s4, s34
	s_addc_u32 s99, s5, s35
	s_add_i32 m0, s101, 0x2000
	s_nop 0
	global_load_lds_dwordx4 v162, s[98:99]
	s_add_i32 m0, s101, 0x4000
	s_nop 0
	global_load_lds_dwordx4 v162, s[42:43]
	s_add_u32 s98, s42, s34
	s_addc_u32 s99, s43, s35
	s_add_i32 m0, s101, 0x6000
	s_nop 0
	global_load_lds_dwordx4 v162, s[98:99]
.LBB0_635:
	s_add_i32 s23, s8, 1
	s_cmp_lt_i32 s8, s24
	s_cselect_b64 s[4:5], -1, 0
	s_cmp_lt_i32 s23, s12
	s_cselect_b64 s[42:43], -1, 0
	s_and_b64 s[4:5], s[4:5], s[42:43]
	s_sub_i32 s25, s25, 64
	s_sub_i32 s26, s26, 64
	s_addk_i32 s27, 0x4000
	s_add_i32 s28, s28, 0x8000
	s_and_b64 vcc, exec, s[4:5]
	s_cbranch_vccnz .LBB0_627
.LBB0_637:
	v_cndmask_b32_e64 v204, v194, v233, s[0:1]
	s_waitcnt lgkmcnt(0)
	v_mfma_f32_32x32x16_f16 v[82:97], v[66:69], v[150:153], 0
	v_sub_f32_e32 v114, v114, v204
	v_exp_f32_e32 v217, v114
	v_sub_f32_e32 v115, v115, v204
	v_exp_f32_e32 v218, v115
	v_sub_f32_e32 v115, v116, v204
	v_exp_f32_e32 v219, v115
	v_sub_f32_e32 v115, v117, v204
	v_mfma_f32_32x32x16_f16 v[66:81], v[70:73], v[150:153], 0
	v_exp_f32_e32 v220, v115
	v_sub_f32_e32 v115, v118, v204
	v_add_f32_e32 v114, 0, v217
	v_exp_f32_e32 v221, v115
	v_sub_f32_e32 v115, v119, v204
	v_add_f32_e32 v114, v218, v114
	v_exp_f32_e32 v224, v115
	v_mfma_f32_32x32x16_f16 v[82:97], v[196:199], v[158:161], v[82:97]
	v_sub_f32_e32 v115, v120, v204
	v_add_f32_e32 v114, v219, v114
	v_exp_f32_e32 v225, v115
	v_sub_f32_e32 v115, v121, v204
	v_add_f32_e32 v114, v220, v114
	v_exp_f32_e32 v226, v115
	v_add_f32_e32 v114, v221, v114
	v_mfma_f32_32x32x16_f16 v[66:81], v[200:203], v[158:161], v[66:81]
	ds_read_b128 v[196:199], v205 offset:512
	ds_read_b128 v[200:203], v205 offset:8704
	ds_read_b128 v[208:211], v216 offset:512
	ds_read_b128 v[212:215], v216 offset:8704
	v_add_f32_e32 v114, v224, v114
	v_add_f32_e32 v114, v225, v114
	v_add_f32_e32 v227, v226, v114
	v_sub_f32_e32 v122, v122, v204
	v_sub_f32_e32 v123, v123, v204
	v_sub_f32_e32 v98, v98, v204
	s_waitcnt lgkmcnt(0)
	v_mfma_f32_32x32x16_f16 v[82:97], v[196:199], v[142:145], v[82:97]
	v_sub_f32_e32 v99, v99, v204
	v_mfma_f32_32x32x16_f16 v[66:81], v[200:203], v[142:145], v[66:81]
	ds_read_b128 v[114:117], v205 offset:1024
	ds_read_b128 v[118:121], v205 offset:9216
	ds_read_b128 v[196:199], v216 offset:1024
	ds_read_b128 v[200:203], v216 offset:9216
	v_mfma_f32_32x32x16_f16 v[82:97], v[208:211], v[154:157], v[82:97]
	v_exp_f32_e32 v208, v122
	v_exp_f32_e32 v209, v123
	v_sub_f32_e32 v123, v124, v204
	v_exp_f32_e32 v210, v123
	v_sub_f32_e32 v123, v125, v204
	v_exp_f32_e32 v211, v123
	v_sub_f32_e32 v123, v126, v204
	v_mfma_f32_32x32x16_f16 v[66:81], v[212:215], v[154:157], v[66:81]
	v_add_f32_e32 v122, v208, v227
	v_exp_f32_e32 v212, v123
	v_sub_f32_e32 v123, v127, v204
	v_add_f32_e32 v122, v209, v122
	v_exp_f32_e32 v213, v123
	v_sub_f32_e32 v123, v128, v204
	v_add_f32_e32 v122, v210, v122
	s_waitcnt lgkmcnt(0)
	v_mfma_f32_32x32x16_f16 v[82:97], v[114:117], v[138:141], v[82:97]
	v_exp_f32_e32 v214, v123
	v_sub_f32_e32 v123, v129, v204
	v_add_f32_e32 v122, v211, v122
	v_exp_f32_e32 v215, v123
	v_add_f32_e32 v122, v212, v122
	v_add_f32_e32 v122, v213, v122
	v_add_f32_e32 v122, v214, v122
	v_mfma_f32_32x32x16_f16 v[66:81], v[118:121], v[138:141], v[66:81]
	v_add_f32_e32 v227, v215, v122
	ds_read_b128 v[114:117], v205 offset:1536
	ds_read_b128 v[118:121], v205 offset:9728
	ds_read_b128 v[122:125], v216 offset:1536
	ds_read_b128 v[126:129], v216 offset:9728
	v_add_u32_e32 v205, s7, v192
	v_mfma_f32_32x32x16_f16 v[82:97], v[196:199], v[146:149], v[82:97]
	v_exp_f32_e32 v196, v98
	v_exp_f32_e32 v197, v99
	v_sub_f32_e32 v99, v100, v204
	v_exp_f32_e32 v198, v99
	v_sub_f32_e32 v99, v101, v204
	v_exp_f32_e32 v199, v99
	v_sub_f32_e32 v99, v102, v204
	v_mfma_f32_32x32x16_f16 v[66:81], v[200:203], v[146:149], v[66:81]
	v_add_f32_e32 v98, v196, v227
	v_exp_f32_e32 v200, v99
	v_sub_f32_e32 v99, v103, v204
	v_add_f32_e32 v98, v197, v98
	v_exp_f32_e32 v201, v99
	v_sub_f32_e32 v99, v104, v204
	v_add_f32_e32 v98, v198, v98
	s_waitcnt lgkmcnt(0)
; #define SBAR() __builtin_amdgcn_sched_barrier(0)
; DI void pv_max(f32x16 (&o)[4], unsigned vb0, unsigned vb1, const f32x16& p0, const f32x16& p1, const f32x16& n0, const f32x16& n1, float& pm) {
;   f16x8 pb[4]; pb[0] = pack8(p0, 0); pb[1] = pack8(p0, 1); pb[2] = pack8(p1, 0); pb[3] = pack8(p1, 1);
;   VFrag fa;
;   float mx = n0[0];
;   pv_rd<0>(fa, vb0, vb1);
;   asm volatile("s_waitcnt lgkmcnt(0)" ::: "memory"); SBAR();
;   pv_mm(o[0], fa, pb);
;   pv_rd<1>(fa, vb0, vb1);
; #pragma unroll
;   for (int r = 1; r < 8; ++r) mx = fmaxf(mx, n0[r]);
;   asm volatile("s_waitcnt lgkmcnt(0)" ::: "memory"); SBAR();
;   pv_mm(o[1], fa, pb);
;   pv_rd<2>(fa, vb0, vb1);
; #pragma unroll
;   for (int r = 8; r < 16; ++r) mx = fmaxf(mx, n0[r]);
;   asm volatile("s_waitcnt lgkmcnt(0)" ::: "memory"); SBAR();
;   pv_mm(o[2], fa, pb);
;   pv_rd<3>(fa, vb0, vb1);
; #pragma unroll
;   for (int r = 0; r < 8; ++r) mx = fmaxf(mx, n1[r]);
;   asm volatile("s_waitcnt lgkmcnt(0)" ::: "memory"); SBAR();
;   pv_mm(o[3], fa, pb);
; #pragma unroll
;   for (int r = 8; r < 16; ++r) mx = fmaxf(mx, n1[r]);
;   pm = mx;
; }
	v_mfma_f32_32x32x16_f16 v[82:97], v[114:117], v[130:133], v[82:97]
	v_exp_f32_e32 v202, v99
	v_sub_f32_e32 v99, v105, v204
	v_add_f32_e32 v98, v199, v98
	v_exp_f32_e32 v203, v99
	v_sub_f32_e32 v99, v106, v204
	v_add_f32_e32 v98, v200, v98
	v_add_f32_e32 v98, v201, v98
	v_mfma_f32_32x32x16_f16 v[66:81], v[118:121], v[130:133], v[66:81]
	v_exp_f32_e32 v118, v99
	v_sub_f32_e32 v99, v107, v204
	v_exp_f32_e32 v119, v99
	v_sub_f32_e32 v99, v108, v204
	v_add_f32_e32 v98, v202, v98
	v_exp_f32_e32 v120, v99
	v_sub_f32_e32 v99, v109, v204
	v_add_f32_e32 v98, v203, v98
	v_exp_f32_e32 v121, v99
	v_sub_f32_e32 v99, v110, v204
	v_mfma_f32_32x32x16_f16 v[82:97], v[122:125], v[134:137], v[82:97]
	v_add_f32_e32 v98, v118, v98
	v_exp_f32_e32 v122, v99
	v_sub_f32_e32 v99, v111, v204
	v_add_f32_e32 v98, v119, v98
	v_exp_f32_e32 v123, v99
	v_sub_f32_e32 v99, v112, v204
	v_add_f32_e32 v98, v120, v98
	v_exp_f32_e32 v124, v99
	v_sub_f32_e32 v99, v113, v204
	v_add_f32_e32 v98, v121, v98
	v_exp_f32_e32 v125, v99
	v_add_f32_e32 v98, v122, v98
	v_add_f32_e32 v98, v123, v98
	v_add_f32_e32 v98, v124, v98
	v_add_f32_e32 v98, v125, v98
	v_add_f32_e32 v195, v195, v98
	v_add_u32_e32 v204, s7, v1
	ds_read_b64_tr_b16 v[98:99], v204 offset:0
	ds_read_b64_tr_b16 v[100:101], v205 offset:0x800
	ds_read_b64_tr_b16 v[102:103], v204 offset:0x1000
	v_mfma_f32_32x32x16_f16 v[66:81], v[126:129], v[134:137], v[66:81]
	ds_read_b64_tr_b16 v[104:105], v205 offset:0x1800
	ds_read_b64_tr_b16 v[106:107], v204 offset:0x2000
	ds_read_b64_tr_b16 v[108:109], v205 offset:0x2800
	ds_read_b64_tr_b16 v[110:111], v204 offset:0x3000
	ds_read_b64_tr_b16 v[112:113], v205 offset:0x3800
	s_waitcnt lgkmcnt(0)
	v_cvt_pk_f16_f32 v117, v225, v226
	v_cvt_pk_f16_f32 v116, v221, v224
	v_cvt_pk_f16_f32 v115, v219, v220
	v_cvt_pk_f16_f32 v114, v217, v218
	s_nop 1
	v_mfma_f32_32x32x16_f16 v[50:65], v[98:101], v[114:117], v[50:65]
	v_cvt_pk_f16_f32 v101, v214, v215
	v_cvt_pk_f16_f32 v100, v212, v213
	v_cvt_pk_f16_f32 v99, v210, v211
	v_cvt_pk_f16_f32 v98, v208, v209
	s_nop 1
	v_mfma_f32_32x32x16_f16 v[50:65], v[102:105], v[98:101], v[50:65]
	v_cvt_pk_f16_f32 v105, v202, v203
	v_cvt_pk_f16_f32 v104, v200, v201
	v_cvt_pk_f16_f32 v103, v198, v199
	v_cvt_pk_f16_f32 v102, v196, v197
	v_max_f32_e32 v196, v83, v83
	v_max_f32_e32 v197, v82, v82
	v_max_f32_e32 v196, v197, v196
	v_mfma_f32_32x32x16_f16 v[50:65], v[106:109], v[102:105], v[50:65]
	v_cvt_pk_f16_f32 v109, v124, v125
	v_cvt_pk_f16_f32 v108, v122, v123
	v_cvt_pk_f16_f32 v107, v120, v121
	v_cvt_pk_f16_f32 v106, v118, v119
	v_max3_f32 v196, v196, v84, v85
	v_max3_f32 v196, v196, v86, v87
	v_max3_f32 v196, v196, v88, v89
	v_mfma_f32_32x32x16_f16 v[50:65], v[110:113], v[106:109], v[50:65]
	ds_read_b64_tr_b16 v[110:111], v204 offset:0x200
	ds_read_b64_tr_b16 v[112:113], v205 offset:0xa00
	ds_read_b64_tr_b16 v[118:119], v204 offset:0x1200
	ds_read_b64_tr_b16 v[120:121], v205 offset:0x1a00
	ds_read_b64_tr_b16 v[122:123], v204 offset:0x2200
	ds_read_b64_tr_b16 v[124:125], v205 offset:0x2a00
	ds_read_b64_tr_b16 v[126:127], v204 offset:0x3200
	ds_read_b64_tr_b16 v[128:129], v205 offset:0x3a00
	s_waitcnt lgkmcnt(0)
	s_nop 0
	v_mfma_f32_32x32x16_f16 v[34:49], v[110:113], v[114:117], v[34:49]
	ds_read_b64_tr_b16 v[110:111], v204 offset:0x400
	ds_read_b64_tr_b16 v[112:113], v205 offset:0xc00
	v_max3_f32 v196, v196, v90, v91
	v_max3_f32 v196, v196, v92, v93
	v_max3_f32 v196, v196, v94, v95
	v_max3_f32 v196, v196, v96, v97
	v_mfma_f32_32x32x16_f16 v[34:49], v[118:121], v[98:101], v[34:49]
	ds_read_b64_tr_b16 v[118:119], v204 offset:0x1400
	ds_read_b64_tr_b16 v[120:121], v205 offset:0x1c00
	v_mfma_f32_32x32x16_f16 v[34:49], v[122:125], v[102:105], v[34:49]
	ds_read_b64_tr_b16 v[122:123], v204 offset:0x2400
	ds_read_b64_tr_b16 v[124:125], v205 offset:0x2c00
	v_mfma_f32_32x32x16_f16 v[34:49], v[126:129], v[106:109], v[34:49]
	ds_read_b64_tr_b16 v[126:127], v204 offset:0x3400
	ds_read_b64_tr_b16 v[128:129], v205 offset:0x3c00
	s_waitcnt lgkmcnt(0)
	v_mfma_f32_32x32x16_f16 v[18:33], v[110:113], v[114:117], v[18:33]
	ds_read_b64_tr_b16 v[110:111], v204 offset:0x600
	ds_read_b64_tr_b16 v[112:113], v205 offset:0xe00
	v_max3_f32 v196, v196, v66, v67
	v_max3_f32 v196, v196, v68, v69
	v_max3_f32 v196, v196, v70, v71
	v_max3_f32 v196, v196, v72, v73
	v_mfma_f32_32x32x16_f16 v[18:33], v[118:121], v[98:101], v[18:33]
	ds_read_b64_tr_b16 v[118:119], v204 offset:0x1600
	ds_read_b64_tr_b16 v[120:121], v205 offset:0x1e00
	v_mfma_f32_32x32x16_f16 v[18:33], v[122:125], v[102:105], v[18:33]
	ds_read_b64_tr_b16 v[122:123], v204 offset:0x2600
	ds_read_b64_tr_b16 v[124:125], v205 offset:0x2e00
	v_mfma_f32_32x32x16_f16 v[18:33], v[126:129], v[106:109], v[18:33]
	ds_read_b64_tr_b16 v[126:127], v204 offset:0x3600
	ds_read_b64_tr_b16 v[128:129], v205 offset:0x3e00
	s_waitcnt lgkmcnt(0)
	v_mfma_f32_32x32x16_f16 v[2:17], v[110:113], v[114:117], v[2:17]
	v_max3_f32 v110, v196, v74, v75
	v_max3_f32 v110, v110, v76, v77
	v_max3_f32 v110, v110, v78, v79
	s_sub_i32 s0, s62, s22
	v_mfma_f32_32x32x16_f16 v[2:17], v[118:121], v[98:101], v[2:17]
	v_max3_f32 v98, v110, v80, v81
	v_mov_b32_e32 v100, v98
	v_lshrrev_b32_e32 v99, s0, v193
	s_nop 0
	v_permlane32_swap_b32_e32 v98, v100
	v_and_b32_e32 v99, 1, v99
	v_max_f32_e32 v100, v100, v100
	v_mfma_f32_32x32x16_f16 v[2:17], v[122:125], v[102:105], v[2:17]
	v_max_f32_e32 v98, v98, v98
	v_max_f32_e32 v98, v98, v100
	v_cmp_eq_u32_e64 s[0:1], 1, v99
	s_nop 1
	v_cndmask_b32_e64 v98, v232, v98, s[0:1]
	v_sub_f32_e32 v99, v98, v194
	v_mfma_f32_32x32x16_f16 v[2:17], v[126:129], v[106:109], v[2:17]
	v_cmp_ge_f32_e32 vcc, s73, v99
	s_cmp_eq_u64 vcc, exec
	s_cbranch_scc1 .LBB0_639
; DI float fexp2(float x) { return __builtin_amdgcn_exp2f(x); }
; DI void osm_decide(float pmn, float& m, float& l, f32x16 (&o)[4]) {
;   if (!__all(pmn - m <= THR)) {
;     float mn = fmaxf(m, pmn); float alpha = fexp2(m - mn); m = mn; l *= alpha;
; #pragma unroll
;     for (int d = 0; d < 4; ++d)
; #pragma unroll
;       for (int r = 0; r < 16; ++r) o[d][r] *= alpha;
;   }
; }
	v_max_f32_e32 v98, v98, v98
	v_max_f32_e32 v99, v194, v194
	v_max_f32_e32 v99, v99, v98
	v_sub_f32_e32 v98, v194, v99
	v_exp_f32_e32 v98, v98
	v_mov_b32_e32 v194, v99
	v_mul_f32_e32 v195, v195, v98
	v_pk_mul_f32 v[64:65], v[64:65], v[98:99] op_sel_hi:[1,0]
	v_pk_mul_f32 v[62:63], v[62:63], v[98:99] op_sel_hi:[1,0]
	v_pk_mul_f32 v[60:61], v[60:61], v[98:99] op_sel_hi:[1,0]
	v_pk_mul_f32 v[58:59], v[58:59], v[98:99] op_sel_hi:[1,0]
	v_pk_mul_f32 v[56:57], v[56:57], v[98:99] op_sel_hi:[1,0]
	v_pk_mul_f32 v[54:55], v[54:55], v[98:99] op_sel_hi:[1,0]
	v_pk_mul_f32 v[52:53], v[52:53], v[98:99] op_sel_hi:[1,0]
	v_pk_mul_f32 v[50:51], v[50:51], v[98:99] op_sel_hi:[1,0]
	v_pk_mul_f32 v[48:49], v[48:49], v[98:99] op_sel_hi:[1,0]
	v_pk_mul_f32 v[46:47], v[46:47], v[98:99] op_sel_hi:[1,0]
	v_pk_mul_f32 v[44:45], v[44:45], v[98:99] op_sel_hi:[1,0]
	v_pk_mul_f32 v[42:43], v[42:43], v[98:99] op_sel_hi:[1,0]
	v_pk_mul_f32 v[40:41], v[40:41], v[98:99] op_sel_hi:[1,0]
	v_pk_mul_f32 v[38:39], v[38:39], v[98:99] op_sel_hi:[1,0]
	v_pk_mul_f32 v[36:37], v[36:37], v[98:99] op_sel_hi:[1,0]
	v_pk_mul_f32 v[34:35], v[34:35], v[98:99] op_sel_hi:[1,0]
	v_pk_mul_f32 v[32:33], v[32:33], v[98:99] op_sel_hi:[1,0]
	v_pk_mul_f32 v[30:31], v[30:31], v[98:99] op_sel_hi:[1,0]
	v_pk_mul_f32 v[28:29], v[28:29], v[98:99] op_sel_hi:[1,0]
	v_pk_mul_f32 v[26:27], v[26:27], v[98:99] op_sel_hi:[1,0]
	v_pk_mul_f32 v[24:25], v[24:25], v[98:99] op_sel_hi:[1,0]
	v_pk_mul_f32 v[22:23], v[22:23], v[98:99] op_sel_hi:[1,0]
	v_pk_mul_f32 v[20:21], v[20:21], v[98:99] op_sel_hi:[1,0]
	v_pk_mul_f32 v[18:19], v[18:19], v[98:99] op_sel_hi:[1,0]
	v_pk_mul_f32 v[16:17], v[16:17], v[98:99] op_sel_hi:[1,0]
	v_pk_mul_f32 v[14:15], v[14:15], v[98:99] op_sel_hi:[1,0]
	v_pk_mul_f32 v[12:13], v[12:13], v[98:99] op_sel_hi:[1,0]
	v_pk_mul_f32 v[10:11], v[10:11], v[98:99] op_sel_hi:[1,0]
	v_pk_mul_f32 v[8:9], v[8:9], v[98:99] op_sel_hi:[1,0]
	v_pk_mul_f32 v[6:7], v[6:7], v[98:99] op_sel_hi:[1,0]
	v_pk_mul_f32 v[4:5], v[4:5], v[98:99] op_sel_hi:[1,0]
	v_pk_mul_f32 v[2:3], v[2:3], v[98:99] op_sel_hi:[1,0]

; #define VWAIT(n) asm volatile("s_waitcnt vmcnt(" #n ")" ::: "memory")
; DI void ring_wait4(int rem) {
;   if (rem >= 3) VWAIT(12); else if (rem == 2) VWAIT(8); else if (rem == 1) VWAIT(4); else VWAIT(0);
; }
.Lvm_slow1:
	s_add_i32 s0, s17, -2
	s_cmp_lt_i32 s0, 3
	s_mov_b64 s[0:1], -1
	s_cbranch_scc0 .LBB0_704
	s_cmp_gt_i32 s17, 3
	s_cbranch_scc0 .LBB0_698
	s_waitcnt vmcnt(8)
	s_mov_b64 s[0:1], 0

; #define VWAIT(n) asm volatile("s_waitcnt vmcnt(" #n ")" ::: "memory")
; DI void ring_wait4(int rem) {
;   if (rem >= 3) VWAIT(12); else if (rem == 2) VWAIT(8); else if (rem == 1) VWAIT(4); else VWAIT(0);
; }
.LBB0_704:
	s_and_b64 vcc, exec, s[0:1]
	s_cbranch_vccz .LBB0_706
	s_waitcnt vmcnt(12)
	s_branch .LBB0_706

; #define VWAIT(n) asm volatile("s_waitcnt vmcnt(" #n ")" ::: "memory")
; DI void ring_wait4(int rem) {
;   if (rem >= 3) VWAIT(12); else if (rem == 2) VWAIT(8); else if (rem == 1) VWAIT(4); else VWAIT(0);
; }
.LBB0_695:
	s_sub_i32 s17, s18, s5
	s_cmp_lg_u32 s17, 3
	s_cbranch_scc1 .Lvm_slow1
	s_waitcnt vmcnt(4)

; #define MFMA(a, b, c) __builtin_amdgcn_mfma_f32_32x32x16_f16((a), (b), (c), 0, 0, 0)
; #define QK_LD(dst, s0) do { dst[0] = *(const f16x8*)(Kst + kbe + 512 * ((s0) >> 1)); dst[1] = *(const f16x8*)(Kst + kbe + 512 * ((s0) >> 1) + 8192); \
;     dst[2] = *(const f16x8*)(Kst + kbo + 512 * ((s0) >> 1)); dst[3] = *(const f16x8*)(Kst + kbo + 512 * ((s0) >> 1) + 8192); } while (0)
; #define QK_LD(dst, s0) do { dst[0] = *(const f16x8*)(Kst + kbe + 512 * ((s0) >> 1)); dst[1] = *(const f16x8*)(Kst + kbe + 512 * ((s0) >> 1) + 8192); \
;     dst[2] = *(const f16x8*)(Kst + kbo + 512 * ((s0) >> 1)); dst[3] = *(const f16x8*)(Kst + kbo + 512 * ((s0) >> 1) + 8192); } while (0)
; #define EXP8(c, b0) do { _Pragma("unroll") for (int j_ = 0; j_ < 8; ++j_) { c[(b0) + j_] = fexp2(c[(b0) + j_] - me); s_ += c[(b0) + j_]; } } while (0)
; DI void qk_exp(f32x16& n0, f32x16& n1, const char* Kst, const f16x8 (&qf)[8], unsigned kbe, unsigned kbo, f32x16& c0, f32x16& c1, float me, float& ps) {
;   const f32x16 zero = {0.f, 0.f, 0.f, 0.f, 0.f, 0.f, 0.f, 0.f, 0.f, 0.f, 0.f, 0.f, 0.f, 0.f, 0.f, 0.f};
;   f16x8 ka[4], kb[4];
;     ...
;   float s_ = 0.f;
;   QK_LD(ka, 0);
;   n0 = MFMA(ka[0], qf[0], zero); n1 = MFMA(ka[1], qf[0], zero); n0 = MFMA(ka[2], qf[1], n0); n1 = MFMA(ka[3], qf[1], n1);
;   QK_LD(kb, 2);
;   EXP8(c0, 0);
;   n0 = MFMA(kb[0], qf[2], n0); n1 = MFMA(kb[1], qf[2], n1); n0 = MFMA(kb[2], qf[3], n0); n1 = MFMA(kb[3], qf[3], n1);
;   QK_LD(ka, 4);
;   EXP8(c0, 8);
;   n0 = MFMA(ka[0], qf[4], n0); n1 = MFMA(ka[1], qf[4], n1); n0 = MFMA(ka[2], qf[5], n0); n1 = MFMA(ka[3], qf[5], n1);
;   QK_LD(kb, 6);
;   EXP8(c1, 0);
;   n0 = MFMA(kb[0], qf[6], n0); n1 = MFMA(kb[1], qf[6], n1); n0 = MFMA(kb[2], qf[7], n0); n1 = MFMA(kb[3], qf[7], n1);
;   EXP8(c1, 8);
;   ps = s_;
;     ...
; }
.LBB0_709:
	s_cmp_ge_i32 s18, s14
	s_cbranch_scc0 .LBB0_711
	s_mul_i32 s1, s21, 0x3000
	s_mul_hi_i32 s0, s21, 0x3000
	s_add_u32 s25, s61, s1
	s_addc_u32 s27, s3, s0
	s_add_u32 s0, s25, s6
	s_addc_u32 s1, s27, 0
	s_add_u32 s26, s25, s7
	s_addc_u32 s27, s27, 0
	s_add_i32 s101, s20, s60
	s_mov_b32 m0, s101
	s_nop 0
	global_load_lds_dwordx4 v206, s[0:1]
	s_add_u32 s98, s0, s86
	s_addc_u32 s99, s1, s87
	s_add_i32 m0, s101, 0x2000
	s_nop 0
	global_load_lds_dwordx4 v206, s[98:99]
	s_add_i32 m0, s101, 0x4000
	s_mov_b64 s[0:1], 0
	global_load_lds_dwordx4 v206, s[26:27]
	s_add_u32 s98, s26, s86
	s_addc_u32 s99, s27, s87
	s_add_i32 m0, s101, 0x6000
	s_nop 0
	global_load_lds_dwordx4 v206, s[98:99]
	s_branch .LBB0_716
.LBB0_708:
	s_mov_b32 s18, s20
	s_and_b32 s20, s24, 0x18000
	s_cmp_gt_i32 s18, 1
	s_mov_b64 s[0:1], -1
	s_cbranch_scc0 .LBB0_714
	s_branch .LBB0_709
.LBB0_717:
	s_mov_b32 s20, s18
	s_branch .LBB0_718
.LBB0_711:
	s_mul_i32 s1, s22, 0x3000
	s_mul_hi_i32 s0, s22, 0x3000
	s_add_u32 s25, s61, s1
	s_addc_u32 s27, s3, s0
	s_add_u32 s0, s25, s8
	s_addc_u32 s1, s27, 0
	s_add_u32 s26, s25, s9
	s_addc_u32 s27, s27, 0
	s_add_i32 s101, s20, s60
	s_mov_b32 m0, s101
	s_nop 0
	global_load_lds_dwordx4 v206, s[0:1]
	s_add_u32 s98, s0, s86
	s_addc_u32 s99, s1, s87
	s_add_i32 m0, s101, 0x2000
	s_nop 0
	global_load_lds_dwordx4 v206, s[98:99]
	s_add_i32 m0, s101, 0x4000
	s_nop 0
	global_load_lds_dwordx4 v206, s[26:27]
	s_add_u32 s98, s26, s86
	s_addc_u32 s99, s27, s87
	s_add_i32 m0, s101, 0x6000
	s_nop 0
	global_load_lds_dwordx4 v206, s[98:99]
	s_branch .LBB0_716
.LBB0_714:
	s_ashr_i32 s25, s23, 31
	s_add_u32 s0, s64, s23
	s_addc_u32 s1, s65, s25
	s_add_u32 s26, s80, s23
	s_addc_u32 s27, s81, s25
	s_add_i32 s101, s20, s60
	s_mov_b32 m0, s101
	s_nop 0
	global_load_lds_dwordx4 v162, s[0:1]
	s_add_u32 s98, s0, s34
	s_addc_u32 s99, s1, s35
	s_add_i32 m0, s101, 0x2000
	s_nop 0
	global_load_lds_dwordx4 v162, s[98:99]
	s_add_i32 m0, s101, 0x4000
	s_nop 0
	global_load_lds_dwordx4 v162, s[26:27]
	s_add_u32 s98, s26, s34
	s_addc_u32 s99, s27, s35
	s_add_i32 m0, s101, 0x6000
	s_nop 0
	global_load_lds_dwordx4 v162, s[98:99]
.LBB0_716:
	s_add_i32 s20, s18, 1
	s_cmp_lt_i32 s18, s17
	s_cselect_b64 s[0:1], -1, 0
	s_cmp_lt_i32 s20, s12
	s_cselect_b64 s[26:27], -1, 0
	s_and_b64 s[0:1], s[0:1], s[26:27]
	s_sub_i32 s21, s21, 64
	s_sub_i32 s22, s22, 64
	s_addk_i32 s23, 0x4000
	s_add_i32 s24, s24, 0x8000
	s_and_b64 vcc, exec, s[0:1]
	s_cbranch_vccnz .LBB0_708
.LBB0_718:
	s_lshl_b32 s0, s19, 15
	s_and_b32 s19, s0, 0x18000
	v_sub_f32_e32 v66, v66, v191
	s_waitcnt lgkmcnt(0)
	v_mfma_f32_32x32x16_f16 v[114:129], v[98:101], v[150:153], 0
	v_exp_f32_e32 v214, v66
	v_sub_f32_e32 v67, v67, v191
	v_exp_f32_e32 v215, v67
	v_sub_f32_e32 v67, v68, v191
	v_exp_f32_e32 v216, v67
	v_sub_f32_e32 v67, v69, v191
	v_exp_f32_e32 v217, v67
	v_mfma_f32_32x32x16_f16 v[98:113], v[102:105], v[150:153], 0
	v_sub_f32_e32 v67, v70, v191
	v_add_f32_e32 v66, 0, v214
	v_exp_f32_e32 v218, v67
	v_sub_f32_e32 v67, v71, v191
	v_add_f32_e32 v66, v215, v66
	v_exp_f32_e32 v219, v67
	v_sub_f32_e32 v67, v72, v191
	v_mfma_f32_32x32x16_f16 v[114:129], v[194:197], v[158:161], v[114:129]
	v_add_f32_e32 v66, v216, v66
	v_exp_f32_e32 v220, v67
	v_sub_f32_e32 v67, v73, v191
	v_add_f32_e32 v66, v217, v66
	v_exp_f32_e32 v221, v67
	v_add_f32_e32 v66, v218, v66
	v_add_f32_e32 v66, v219, v66
	v_mfma_f32_32x32x16_f16 v[98:113], v[198:201], v[158:161], v[98:113]
	ds_read_b128 v[194:197], v212 offset:512
	ds_read_b128 v[198:201], v212 offset:8704
	ds_read_b128 v[202:205], v213 offset:512
	ds_read_b128 v[208:211], v213 offset:8704
	v_add_f32_e32 v66, v220, v66
	v_add_f32_e32 v224, v221, v66
	v_sub_f32_e32 v74, v74, v191
	v_sub_f32_e32 v75, v75, v191
	v_sub_f32_e32 v82, v82, v191
	v_sub_f32_e32 v83, v83, v191
	s_waitcnt lgkmcnt(0)
	v_mfma_f32_32x32x16_f16 v[114:129], v[194:197], v[142:145], v[114:129]
	s_lshl_b32 s0, s5, 15
	s_and_b32 s21, s0, 0x18000
	v_mfma_f32_32x32x16_f16 v[98:113], v[198:201], v[142:145], v[98:113]
	ds_read_b128 v[66:69], v212 offset:1024
	ds_read_b128 v[70:73], v212 offset:9216
	ds_read_b128 v[194:197], v213 offset:1024
	ds_read_b128 v[198:201], v213 offset:9216
	v_mfma_f32_32x32x16_f16 v[114:129], v[202:205], v[154:157], v[114:129]
	v_exp_f32_e32 v202, v74
	v_exp_f32_e32 v203, v75
	v_sub_f32_e32 v75, v76, v191
	v_exp_f32_e32 v204, v75
	v_sub_f32_e32 v75, v77, v191
	v_exp_f32_e32 v205, v75
	v_sub_f32_e32 v75, v78, v191
	v_mfma_f32_32x32x16_f16 v[98:113], v[208:211], v[154:157], v[98:113]
	v_add_f32_e32 v74, v202, v224
	v_exp_f32_e32 v208, v75
	v_sub_f32_e32 v75, v79, v191
	v_add_f32_e32 v74, v203, v74
	v_exp_f32_e32 v209, v75
	v_sub_f32_e32 v75, v80, v191
	v_add_f32_e32 v74, v204, v74
	s_waitcnt lgkmcnt(0)
	v_mfma_f32_32x32x16_f16 v[114:129], v[66:69], v[138:141], v[114:129]
	v_exp_f32_e32 v210, v75
	v_sub_f32_e32 v75, v81, v191
	v_add_f32_e32 v74, v205, v74
	v_exp_f32_e32 v211, v75
	v_add_f32_e32 v74, v208, v74
	v_add_f32_e32 v74, v209, v74
	v_add_f32_e32 v74, v210, v74
	v_mfma_f32_32x32x16_f16 v[98:113], v[70:73], v[138:141], v[98:113]
	v_add_f32_e32 v224, v211, v74
	ds_read_b128 v[66:69], v212 offset:1536
	ds_read_b128 v[70:73], v212 offset:9728
	ds_read_b128 v[74:77], v213 offset:1536
	ds_read_b128 v[78:81], v213 offset:9728
	v_mfma_f32_32x32x16_f16 v[114:129], v[194:197], v[146:149], v[114:129]
	v_exp_f32_e32 v194, v82
	v_exp_f32_e32 v195, v83
	v_sub_f32_e32 v83, v84, v191
	v_exp_f32_e32 v196, v83
	v_sub_f32_e32 v83, v85, v191
	v_exp_f32_e32 v197, v83
	v_sub_f32_e32 v83, v86, v191
	v_add_f32_e32 v82, v194, v224
	v_exp_f32_e32 v86, v83
	v_sub_f32_e32 v83, v87, v191
	v_add_f32_e32 v82, v195, v82
	v_exp_f32_e32 v87, v83
	v_sub_f32_e32 v83, v88, v191
	v_add_f32_e32 v82, v196, v82
	v_exp_f32_e32 v88, v83
	v_sub_f32_e32 v83, v89, v191
	v_mfma_f32_32x32x16_f16 v[98:113], v[198:201], v[146:149], v[98:113]
	v_add_f32_e32 v82, v197, v82
	v_exp_f32_e32 v89, v83
	v_add_f32_e32 v82, v86, v82
	v_add_f32_e32 v82, v87, v82
	v_add_f32_e32 v82, v88, v82
	v_add_f32_e32 v82, v89, v82
	v_add_u32_e32 v198, s21, v1
	s_waitcnt lgkmcnt(0)
; #define SBAR() __builtin_amdgcn_sched_barrier(0)
; DI void pv_max(f32x16 (&o)[4], unsigned vb0, unsigned vb1, const f32x16& p0, const f32x16& p1, const f32x16& n0, const f32x16& n1, float& pm) {
;   f16x8 pb[4]; pb[0] = pack8(p0, 0); pb[1] = pack8(p0, 1); pb[2] = pack8(p1, 0); pb[3] = pack8(p1, 1);
;   VFrag fa;
;   float mx = n0[0];
;   pv_rd<0>(fa, vb0, vb1);
;   asm volatile("s_waitcnt lgkmcnt(0)" ::: "memory"); SBAR();
;   pv_mm(o[0], fa, pb);
;   pv_rd<1>(fa, vb0, vb1);
; #pragma unroll
;   for (int r = 1; r < 8; ++r) mx = fmaxf(mx, n0[r]);
;   asm volatile("s_waitcnt lgkmcnt(0)" ::: "memory"); SBAR();
;   pv_mm(o[1], fa, pb);
;   pv_rd<2>(fa, vb0, vb1);
; #pragma unroll
;   for (int r = 8; r < 16; ++r) mx = fmaxf(mx, n0[r]);
;   asm volatile("s_waitcnt lgkmcnt(0)" ::: "memory"); SBAR();
;   pv_mm(o[2], fa, pb);
;   pv_rd<3>(fa, vb0, vb1);
; #pragma unroll
;   for (int r = 0; r < 8; ++r) mx = fmaxf(mx, n1[r]);
;   asm volatile("s_waitcnt lgkmcnt(0)" ::: "memory"); SBAR();
;   pv_mm(o[3], fa, pb);
; #pragma unroll
;   for (int r = 8; r < 16; ++r) mx = fmaxf(mx, n1[r]);
;   pm = mx;
; }
	v_mfma_f32_32x32x16_f16 v[114:129], v[66:69], v[130:133], v[114:129]
	v_sub_f32_e32 v66, v90, v191
	v_exp_f32_e32 v90, v66
	v_sub_f32_e32 v67, v91, v191
	v_exp_f32_e32 v91, v67
	v_sub_f32_e32 v67, v92, v191
	v_exp_f32_e32 v92, v67
	v_sub_f32_e32 v67, v93, v191
	v_exp_f32_e32 v93, v67
	v_sub_f32_e32 v67, v94, v191
	v_add_f32_e32 v66, v90, v82
	v_exp_f32_e32 v94, v67
	v_sub_f32_e32 v67, v95, v191
	v_add_f32_e32 v66, v91, v66
	v_exp_f32_e32 v95, v67
	v_sub_f32_e32 v67, v96, v191
	v_add_f32_e32 v66, v92, v66
	v_exp_f32_e32 v96, v67
	v_sub_f32_e32 v67, v97, v191
	v_mfma_f32_32x32x16_f16 v[98:113], v[70:73], v[130:133], v[98:113]
	v_add_f32_e32 v66, v93, v66
	v_exp_f32_e32 v97, v67
	v_add_f32_e32 v66, v94, v66
	v_add_f32_e32 v66, v95, v66
	v_add_f32_e32 v66, v96, v66
	v_add_f32_e32 v66, v97, v66
	v_add_f32_e32 v193, v193, v66
	ds_read_b64_tr_b16 v[66:67], v198 offset:0
	v_add_u32_e32 v199, s21, v192
	ds_read_b64_tr_b16 v[68:69], v199 offset:0x800
	ds_read_b64_tr_b16 v[70:71], v198 offset:0x1000
	v_mfma_f32_32x32x16_f16 v[114:129], v[74:77], v[134:137], v[114:129]
	ds_read_b64_tr_b16 v[72:73], v199 offset:0x1800
	ds_read_b64_tr_b16 v[74:75], v198 offset:0x2000
	ds_read_b64_tr_b16 v[76:77], v199 offset:0x2800
	v_mfma_f32_32x32x16_f16 v[98:113], v[78:81], v[134:137], v[98:113]
	ds_read_b64_tr_b16 v[78:79], v198 offset:0x3000
	ds_read_b64_tr_b16 v[80:81], v199 offset:0x3800
	s_waitcnt lgkmcnt(0)
	v_cvt_pk_f16_f32 v85, v220, v221
	v_cvt_pk_f16_f32 v84, v218, v219
	v_cvt_pk_f16_f32 v83, v216, v217
	v_cvt_pk_f16_f32 v82, v214, v215
	s_nop 1
	v_mfma_f32_32x32x16_f16 v[50:65], v[66:69], v[82:85], v[50:65]
	v_cvt_pk_f16_f32 v69, v210, v211
	v_cvt_pk_f16_f32 v68, v208, v209
	v_cvt_pk_f16_f32 v67, v204, v205
	v_cvt_pk_f16_f32 v66, v202, v203
	s_nop 1
	v_mfma_f32_32x32x16_f16 v[50:65], v[70:73], v[66:69], v[50:65]
	v_cvt_pk_f16_f32 v73, v88, v89
	v_cvt_pk_f16_f32 v72, v86, v87
	v_cvt_pk_f16_f32 v71, v196, v197
	v_cvt_pk_f16_f32 v70, v194, v195
	v_max_f32_e32 v194, v115, v115
	v_max_f32_e32 v195, v114, v114
	v_max_f32_e32 v194, v195, v194
	v_mfma_f32_32x32x16_f16 v[50:65], v[74:77], v[70:73], v[50:65]
	v_cvt_pk_f16_f32 v77, v96, v97
	v_cvt_pk_f16_f32 v76, v94, v95
	v_cvt_pk_f16_f32 v75, v92, v93
	v_cvt_pk_f16_f32 v74, v90, v91
	v_max3_f32 v194, v194, v116, v117
	v_max3_f32 v194, v194, v118, v119
	v_max3_f32 v194, v194, v120, v121
	v_mfma_f32_32x32x16_f16 v[50:65], v[78:81], v[74:77], v[50:65]
	ds_read_b64_tr_b16 v[78:79], v198 offset:0x200
	ds_read_b64_tr_b16 v[80:81], v199 offset:0xa00
	ds_read_b64_tr_b16 v[86:87], v198 offset:0x1200
	ds_read_b64_tr_b16 v[88:89], v199 offset:0x1a00
	ds_read_b64_tr_b16 v[90:91], v198 offset:0x2200
	ds_read_b64_tr_b16 v[92:93], v199 offset:0x2a00
	ds_read_b64_tr_b16 v[94:95], v198 offset:0x3200
	ds_read_b64_tr_b16 v[96:97], v199 offset:0x3a00
	s_waitcnt lgkmcnt(0)
	s_nop 0
	v_mfma_f32_32x32x16_f16 v[34:49], v[78:81], v[82:85], v[34:49]
	ds_read_b64_tr_b16 v[78:79], v198 offset:0x400
	ds_read_b64_tr_b16 v[80:81], v199 offset:0xc00
	v_max3_f32 v194, v194, v122, v123
	v_max3_f32 v194, v194, v124, v125
	v_max3_f32 v194, v194, v126, v127
	v_max3_f32 v194, v194, v128, v129
	v_mfma_f32_32x32x16_f16 v[34:49], v[86:89], v[66:69], v[34:49]
	ds_read_b64_tr_b16 v[86:87], v198 offset:0x1400
	ds_read_b64_tr_b16 v[88:89], v199 offset:0x1c00
	v_mfma_f32_32x32x16_f16 v[34:49], v[90:93], v[70:73], v[34:49]
	ds_read_b64_tr_b16 v[90:91], v198 offset:0x2400
	ds_read_b64_tr_b16 v[92:93], v199 offset:0x2c00
	v_mfma_f32_32x32x16_f16 v[34:49], v[94:97], v[74:77], v[34:49]
	ds_read_b64_tr_b16 v[94:95], v198 offset:0x3400
	ds_read_b64_tr_b16 v[96:97], v199 offset:0x3c00
	s_waitcnt lgkmcnt(0)
	v_mfma_f32_32x32x16_f16 v[18:33], v[78:81], v[82:85], v[18:33]
	ds_read_b64_tr_b16 v[78:79], v198 offset:0x600
	ds_read_b64_tr_b16 v[80:81], v199 offset:0xe00
	v_max3_f32 v194, v194, v98, v99
	v_max3_f32 v194, v194, v100, v101
	v_max3_f32 v194, v194, v102, v103
	v_max3_f32 v194, v194, v104, v105
	v_mfma_f32_32x32x16_f16 v[18:33], v[86:89], v[66:69], v[18:33]
	ds_read_b64_tr_b16 v[86:87], v198 offset:0x1600
	ds_read_b64_tr_b16 v[88:89], v199 offset:0x1e00
	v_mfma_f32_32x32x16_f16 v[18:33], v[90:93], v[70:73], v[18:33]
	ds_read_b64_tr_b16 v[90:91], v198 offset:0x2600
	ds_read_b64_tr_b16 v[92:93], v199 offset:0x2e00
	v_mfma_f32_32x32x16_f16 v[18:33], v[94:97], v[74:77], v[18:33]
	ds_read_b64_tr_b16 v[94:95], v198 offset:0x3600
	ds_read_b64_tr_b16 v[96:97], v199 offset:0x3e00
	s_waitcnt lgkmcnt(0)
	v_mfma_f32_32x32x16_f16 v[2:17], v[78:81], v[82:85], v[2:17]
	v_mfma_f32_32x32x16_f16 v[2:17], v[86:89], v[66:69], v[2:17]
	v_max3_f32 v66, v194, v106, v107
	v_max3_f32 v66, v66, v108, v109
	v_max3_f32 v66, v66, v110, v111
	v_max3_f32 v66, v66, v112, v113
	v_mov_b32_e32 v67, v66
	s_nop 1
	v_permlane32_swap_b32_e32 v66, v67
	v_mfma_f32_32x32x16_f16 v[2:17], v[90:93], v[70:73], v[2:17]
	v_max_f32_e32 v67, v67, v67
	v_max_f32_e32 v66, v66, v66
	v_max_f32_e32 v66, v66, v67
	v_sub_f32_e32 v67, v66, v191
	v_cmp_ge_f32_e32 vcc, s73, v67
	s_cmp_eq_u64 vcc, exec
	v_mfma_f32_32x32x16_f16 v[2:17], v[94:97], v[74:77], v[2:17]
	s_cbranch_scc1 .LBB0_720
; DI float fexp2(float x) { return __builtin_amdgcn_exp2f(x); }
; #define VWAIT(n) asm volatile("s_waitcnt vmcnt(" #n ")" ::: "memory")
; DI void osm_decide(float pmn, float& m, float& l, f32x16 (&o)[4]) {
;   if (!__all(pmn - m <= THR)) {
;     float mn = fmaxf(m, pmn); float alpha = fexp2(m - mn); m = mn; l *= alpha;
; #pragma unroll
;     for (int d = 0; d < 4; ++d)
; #pragma unroll
;       for (int r = 0; r < 16; ++r) o[d][r] *= alpha;
;   }
; }
; DI void ring_wait4(int rem) {
;   if (rem >= 3) VWAIT(12); else if (rem == 2) VWAIT(8); else if (rem == 1) VWAIT(4); else VWAIT(0);
; }
	v_max_f32_e32 v66, v66, v66
	v_max_f32_e32 v67, v191, v191
	v_max_f32_e32 v67, v67, v66
	v_sub_f32_e32 v66, v191, v67
	v_exp_f32_e32 v66, v66
	v_mov_b32_e32 v191, v67
	v_mul_f32_e32 v193, v193, v66
	v_pk_mul_f32 v[64:65], v[64:65], v[66:67] op_sel_hi:[1,0]
	v_pk_mul_f32 v[62:63], v[62:63], v[66:67] op_sel_hi:[1,0]
	v_pk_mul_f32 v[60:61], v[60:61], v[66:67] op_sel_hi:[1,0]
	v_pk_mul_f32 v[58:59], v[58:59], v[66:67] op_sel_hi:[1,0]
	v_pk_mul_f32 v[56:57], v[56:57], v[66:67] op_sel_hi:[1,0]
	v_pk_mul_f32 v[54:55], v[54:55], v[66:67] op_sel_hi:[1,0]
	v_pk_mul_f32 v[52:53], v[52:53], v[66:67] op_sel_hi:[1,0]
	v_pk_mul_f32 v[50:51], v[50:51], v[66:67] op_sel_hi:[1,0]
	v_pk_mul_f32 v[48:49], v[48:49], v[66:67] op_sel_hi:[1,0]
	v_pk_mul_f32 v[46:47], v[46:47], v[66:67] op_sel_hi:[1,0]
	v_pk_mul_f32 v[44:45], v[44:45], v[66:67] op_sel_hi:[1,0]
	v_pk_mul_f32 v[42:43], v[42:43], v[66:67] op_sel_hi:[1,0]
	v_pk_mul_f32 v[40:41], v[40:41], v[66:67] op_sel_hi:[1,0]
	v_pk_mul_f32 v[38:39], v[38:39], v[66:67] op_sel_hi:[1,0]
	v_pk_mul_f32 v[36:37], v[36:37], v[66:67] op_sel_hi:[1,0]
	v_pk_mul_f32 v[34:35], v[34:35], v[66:67] op_sel_hi:[1,0]
	v_pk_mul_f32 v[32:33], v[32:33], v[66:67] op_sel_hi:[1,0]
	v_pk_mul_f32 v[30:31], v[30:31], v[66:67] op_sel_hi:[1,0]
	v_pk_mul_f32 v[28:29], v[28:29], v[66:67] op_sel_hi:[1,0]
	v_pk_mul_f32 v[26:27], v[26:27], v[66:67] op_sel_hi:[1,0]
	v_pk_mul_f32 v[24:25], v[24:25], v[66:67] op_sel_hi:[1,0]
	v_pk_mul_f32 v[22:23], v[22:23], v[66:67] op_sel_hi:[1,0]
	v_pk_mul_f32 v[20:21], v[20:21], v[66:67] op_sel_hi:[1,0]
	v_pk_mul_f32 v[18:19], v[18:19], v[66:67] op_sel_hi:[1,0]
	v_pk_mul_f32 v[16:17], v[16:17], v[66:67] op_sel_hi:[1,0]
	v_pk_mul_f32 v[14:15], v[14:15], v[66:67] op_sel_hi:[1,0]
	v_pk_mul_f32 v[12:13], v[12:13], v[66:67] op_sel_hi:[1,0]
	v_pk_mul_f32 v[10:11], v[10:11], v[66:67] op_sel_hi:[1,0]
	v_pk_mul_f32 v[8:9], v[8:9], v[66:67] op_sel_hi:[1,0]
	v_pk_mul_f32 v[6:7], v[6:7], v[66:67] op_sel_hi:[1,0]
	v_pk_mul_f32 v[4:5], v[4:5], v[66:67] op_sel_hi:[1,0]
	v_pk_mul_f32 v[2:3], v[2:3], v[66:67] op_sel_hi:[1,0]
.LBB0_720:
	s_sub_i32 s18, s20, s5
	s_cmp_lg_u32 s18, 4
	s_cbranch_scc1 .Lvm_slow2
	s_waitcnt vmcnt(4)

; #define VWAIT(n) asm volatile("s_waitcnt vmcnt(" #n ")" ::: "memory")
; DI void ring_wait4(int rem) {
;   if (rem >= 3) VWAIT(12); else if (rem == 2) VWAIT(8); else if (rem == 1) VWAIT(4); else VWAIT(0);
; }
.LBB0_734:
	s_cmp_ge_i32 s20, s14
	s_cbranch_scc0 .LBB0_736
	s_mul_i32 s1, s23, 0x3000
	s_mul_hi_i32 s0, s23, 0x3000
	s_add_u32 s27, s61, s1
	s_addc_u32 s29, s3, s0
	s_add_u32 s0, s27, s6
	s_addc_u32 s1, s29, 0
	s_add_u32 s28, s27, s7
	s_addc_u32 s29, s29, 0
	s_add_i32 s101, s18, s60
	s_mov_b32 m0, s101
	s_nop 0
	global_load_lds_dwordx4 v206, s[0:1]
	s_add_u32 s98, s0, s86
	s_addc_u32 s99, s1, s87
	s_add_i32 m0, s101, 0x2000
	s_nop 0
	global_load_lds_dwordx4 v206, s[98:99]
	s_add_i32 m0, s101, 0x4000
	s_mov_b64 s[0:1], 0
	global_load_lds_dwordx4 v206, s[28:29]
	s_add_u32 s98, s28, s86
	s_addc_u32 s99, s29, s87
	s_add_i32 m0, s101, 0x6000
	s_nop 0
	global_load_lds_dwordx4 v206, s[98:99]
	s_branch .LBB0_741
.Lvm_slow2:
	s_add_i32 s0, s18, -3
	s_cmp_lt_i32 s0, 3
	s_mov_b64 s[0:1], -1
	s_cbranch_scc0 .LBB0_729
	s_cmp_gt_i32 s18, 4
	s_cbranch_scc0 .LBB0_723
	s_waitcnt vmcnt(8)
	s_mov_b64 s[0:1], 0

; #define MFMA(a, b, c) __builtin_amdgcn_mfma_f32_32x32x16_f16((a), (b), (c), 0, 0, 0)
; #define QK_LD(dst, s0) do { dst[0] = *(const f16x8*)(Kst + kbe + 512 * ((s0) >> 1)); dst[1] = *(const f16x8*)(Kst + kbe + 512 * ((s0) >> 1) + 8192); \
;     dst[2] = *(const f16x8*)(Kst + kbo + 512 * ((s0) >> 1)); dst[3] = *(const f16x8*)(Kst + kbo + 512 * ((s0) >> 1) + 8192); } while (0)
; #define QK_LD(dst, s0) do { dst[0] = *(const f16x8*)(Kst + kbe + 512 * ((s0) >> 1)); dst[1] = *(const f16x8*)(Kst + kbe + 512 * ((s0) >> 1) + 8192); \
;     dst[2] = *(const f16x8*)(Kst + kbo + 512 * ((s0) >> 1)); dst[3] = *(const f16x8*)(Kst + kbo + 512 * ((s0) >> 1) + 8192); } while (0)
; #define EXP8(c, b0) do { _Pragma("unroll") for (int j_ = 0; j_ < 8; ++j_) { c[(b0) + j_] = fexp2(c[(b0) + j_] - me); s_ += c[(b0) + j_]; } } while (0)
; DI void qk_exp(f32x16& n0, f32x16& n1, const char* Kst, const f16x8 (&qf)[8], unsigned kbe, unsigned kbo, f32x16& c0, f32x16& c1, float me, float& ps) {
;   const f32x16 zero = {0.f, 0.f, 0.f, 0.f, 0.f, 0.f, 0.f, 0.f, 0.f, 0.f, 0.f, 0.f, 0.f, 0.f, 0.f, 0.f};
;   f16x8 ka[4], kb[4];
;     ...
;   float s_ = 0.f;
;   QK_LD(ka, 0);
;   n0 = MFMA(ka[0], qf[0], zero); n1 = MFMA(ka[1], qf[0], zero); n0 = MFMA(ka[2], qf[1], n0); n1 = MFMA(ka[3], qf[1], n1);
;   QK_LD(kb, 2);
;   EXP8(c0, 0);
;   n0 = MFMA(kb[0], qf[2], n0); n1 = MFMA(kb[1], qf[2], n1); n0 = MFMA(kb[2], qf[3], n0); n1 = MFMA(kb[3], qf[3], n1);
;   QK_LD(ka, 4);
;   EXP8(c0, 8);
;   n0 = MFMA(ka[0], qf[4], n0); n1 = MFMA(ka[1], qf[4], n1); n0 = MFMA(ka[2], qf[5], n0); n1 = MFMA(ka[3], qf[5], n1);
;   QK_LD(kb, 6);
;   EXP8(c1, 0);
;   n0 = MFMA(kb[0], qf[6], n0); n1 = MFMA(kb[1], qf[6], n1); n0 = MFMA(kb[2], qf[7], n0); n1 = MFMA(kb[3], qf[7], n1);
;   EXP8(c1, 8);
;   ps = s_;
;     ...
; }
.LBB0_733:
	s_mov_b32 s20, s18
	s_and_b32 s18, s26, 0x18000
	s_cmp_gt_i32 s20, 1
	s_mov_b64 s[0:1], -1
	s_cbranch_scc0 .LBB0_739
	s_branch .LBB0_734
.LBB0_742:
	s_mov_b32 s18, s20
	s_branch .LBB0_743
.LBB0_736:
	s_mul_i32 s1, s24, 0x3000
	s_mul_hi_i32 s0, s24, 0x3000
	s_add_u32 s27, s61, s1
	s_addc_u32 s29, s3, s0
	s_add_u32 s0, s27, s8
	s_addc_u32 s1, s29, 0
	s_add_u32 s28, s27, s9
	s_addc_u32 s29, s29, 0
	s_add_i32 s101, s18, s60
	s_mov_b32 m0, s101
	s_nop 0
	global_load_lds_dwordx4 v206, s[0:1]
	s_add_u32 s98, s0, s86
	s_addc_u32 s99, s1, s87
	s_add_i32 m0, s101, 0x2000
	s_nop 0
	global_load_lds_dwordx4 v206, s[98:99]
	s_add_i32 m0, s101, 0x4000
	s_nop 0
	global_load_lds_dwordx4 v206, s[28:29]
	s_add_u32 s98, s28, s86
	s_addc_u32 s99, s29, s87
	s_add_i32 m0, s101, 0x6000
	s_nop 0
	global_load_lds_dwordx4 v206, s[98:99]
	s_branch .LBB0_741
.LBB0_739:
	s_ashr_i32 s27, s25, 31
	s_add_u32 s0, s64, s25
	s_addc_u32 s1, s65, s27
	s_add_u32 s28, s80, s25
	s_addc_u32 s29, s81, s27
	s_add_i32 s101, s18, s60
	s_mov_b32 m0, s101
	s_nop 0
	global_load_lds_dwordx4 v162, s[0:1]
	s_add_u32 s98, s0, s34
	s_addc_u32 s99, s1, s35
	s_add_i32 m0, s101, 0x2000
	s_nop 0
	global_load_lds_dwordx4 v162, s[98:99]
	s_add_i32 m0, s101, 0x4000
	s_nop 0
	global_load_lds_dwordx4 v162, s[28:29]
	s_add_u32 s98, s28, s34
	s_addc_u32 s99, s29, s35
	s_add_i32 m0, s101, 0x6000
	s_nop 0
	global_load_lds_dwordx4 v162, s[98:99]
.LBB0_741:
	s_add_i32 s18, s20, 1
	s_cmp_lt_i32 s20, s22
	s_cselect_b64 s[0:1], -1, 0
	s_cmp_lt_i32 s18, s12
	s_cselect_b64 s[28:29], -1, 0
	s_and_b64 s[0:1], s[0:1], s[28:29]
	s_sub_i32 s23, s23, 64
	s_sub_i32 s24, s24, 64
	s_addk_i32 s25, 0x4000
	s_add_i32 s26, s26, 0x8000
	s_and_b64 vcc, exec, s[0:1]
	s_cbranch_vccnz .LBB0_733
.LBB0_743:
	v_sub_f32_e32 v114, v114, v191
	s_waitcnt lgkmcnt(0)
	v_mfma_f32_32x32x16_f16 v[66:81], v[66:69], v[150:153], 0
	v_exp_f32_e32 v214, v114
	v_sub_f32_e32 v115, v115, v191
	v_exp_f32_e32 v215, v115
	v_sub_f32_e32 v115, v116, v191
	v_exp_f32_e32 v216, v115
	v_sub_f32_e32 v115, v117, v191
	v_exp_f32_e32 v217, v115
	v_mfma_f32_32x32x16_f16 v[82:97], v[82:85], v[150:153], 0
	v_sub_f32_e32 v115, v118, v191
	v_add_f32_e32 v114, 0, v214
	v_exp_f32_e32 v218, v115
	v_sub_f32_e32 v115, v119, v191
	v_add_f32_e32 v114, v215, v114
	v_exp_f32_e32 v219, v115
	v_sub_f32_e32 v115, v120, v191
	v_mfma_f32_32x32x16_f16 v[66:81], v[194:197], v[158:161], v[66:81]
	v_add_f32_e32 v114, v216, v114
	v_exp_f32_e32 v220, v115
	v_sub_f32_e32 v115, v121, v191
	v_add_f32_e32 v114, v217, v114
	v_exp_f32_e32 v221, v115
	v_add_f32_e32 v114, v218, v114
	v_add_f32_e32 v114, v219, v114
	v_mfma_f32_32x32x16_f16 v[82:97], v[198:201], v[158:161], v[82:97]
	ds_read_b128 v[194:197], v212 offset:512
	ds_read_b128 v[198:201], v212 offset:8704
	ds_read_b128 v[202:205], v213 offset:512
	ds_read_b128 v[208:211], v213 offset:8704
	v_add_f32_e32 v114, v220, v114
	v_add_f32_e32 v224, v221, v114
	v_sub_f32_e32 v122, v122, v191
	v_sub_f32_e32 v123, v123, v191
	v_sub_f32_e32 v98, v98, v191
	v_sub_f32_e32 v99, v99, v191
	s_waitcnt lgkmcnt(0)
	v_mfma_f32_32x32x16_f16 v[66:81], v[194:197], v[142:145], v[66:81]
	v_mfma_f32_32x32x16_f16 v[82:97], v[198:201], v[142:145], v[82:97]
	ds_read_b128 v[114:117], v212 offset:1024
	ds_read_b128 v[118:121], v212 offset:9216
	ds_read_b128 v[194:197], v213 offset:1024
	ds_read_b128 v[198:201], v213 offset:9216
	v_mfma_f32_32x32x16_f16 v[66:81], v[202:205], v[154:157], v[66:81]
	v_exp_f32_e32 v202, v122
	v_exp_f32_e32 v203, v123
	v_sub_f32_e32 v123, v124, v191
	v_exp_f32_e32 v204, v123
	v_sub_f32_e32 v123, v125, v191
	v_exp_f32_e32 v205, v123
	v_sub_f32_e32 v123, v126, v191
	v_mfma_f32_32x32x16_f16 v[82:97], v[208:211], v[154:157], v[82:97]
	v_add_f32_e32 v122, v202, v224
	v_exp_f32_e32 v208, v123
	v_sub_f32_e32 v123, v127, v191
	v_add_f32_e32 v122, v203, v122
	v_exp_f32_e32 v209, v123
	v_sub_f32_e32 v123, v128, v191
	v_add_f32_e32 v122, v204, v122
	s_waitcnt lgkmcnt(0)
	v_mfma_f32_32x32x16_f16 v[66:81], v[114:117], v[138:141], v[66:81]
	v_exp_f32_e32 v210, v123
	v_sub_f32_e32 v123, v129, v191
	v_add_f32_e32 v122, v205, v122
	v_exp_f32_e32 v211, v123
	v_add_f32_e32 v122, v208, v122
	v_add_f32_e32 v122, v209, v122
	v_add_f32_e32 v122, v210, v122
	v_mfma_f32_32x32x16_f16 v[82:97], v[118:121], v[138:141], v[82:97]
	v_add_f32_e32 v224, v211, v122
	ds_read_b128 v[114:117], v212 offset:1536
	ds_read_b128 v[118:121], v212 offset:9728
	ds_read_b128 v[122:125], v213 offset:1536
	ds_read_b128 v[126:129], v213 offset:9728
	v_add_u32_e32 v212, s19, v1
	v_add_u32_e32 v213, s19, v192
	v_mfma_f32_32x32x16_f16 v[66:81], v[194:197], v[146:149], v[66:81]
	v_exp_f32_e32 v194, v98
	v_exp_f32_e32 v195, v99
	v_sub_f32_e32 v99, v100, v191
	v_exp_f32_e32 v196, v99
	v_sub_f32_e32 v99, v101, v191
	v_exp_f32_e32 v197, v99
	v_sub_f32_e32 v99, v102, v191
	v_mfma_f32_32x32x16_f16 v[82:97], v[198:201], v[146:149], v[82:97]
	v_add_f32_e32 v98, v194, v224
	v_exp_f32_e32 v198, v99
	v_sub_f32_e32 v99, v103, v191
	v_add_f32_e32 v98, v195, v98
	v_exp_f32_e32 v199, v99
	v_sub_f32_e32 v99, v104, v191
	v_add_f32_e32 v98, v196, v98
	s_waitcnt lgkmcnt(0)
; #define SBAR() __builtin_amdgcn_sched_barrier(0)
; DI void pv_max(f32x16 (&o)[4], unsigned vb0, unsigned vb1, const f32x16& p0, const f32x16& p1, const f32x16& n0, const f32x16& n1, float& pm) {
;   f16x8 pb[4]; pb[0] = pack8(p0, 0); pb[1] = pack8(p0, 1); pb[2] = pack8(p1, 0); pb[3] = pack8(p1, 1);
;   VFrag fa;
;   float mx = n0[0];
;   pv_rd<0>(fa, vb0, vb1);
;   asm volatile("s_waitcnt lgkmcnt(0)" ::: "memory"); SBAR();
;   pv_mm(o[0], fa, pb);
;   pv_rd<1>(fa, vb0, vb1);
; #pragma unroll
;   for (int r = 1; r < 8; ++r) mx = fmaxf(mx, n0[r]);
;   asm volatile("s_waitcnt lgkmcnt(0)" ::: "memory"); SBAR();
;   pv_mm(o[1], fa, pb);
;   pv_rd<2>(fa, vb0, vb1);
; #pragma unroll
;   for (int r = 8; r < 16; ++r) mx = fmaxf(mx, n0[r]);
;   asm volatile("s_waitcnt lgkmcnt(0)" ::: "memory"); SBAR();
;   pv_mm(o[2], fa, pb);
;   pv_rd<3>(fa, vb0, vb1);
; #pragma unroll
;   for (int r = 0; r < 8; ++r) mx = fmaxf(mx, n1[r]);
;   asm volatile("s_waitcnt lgkmcnt(0)" ::: "memory"); SBAR();
;   pv_mm(o[3], fa, pb);
; #pragma unroll
;   for (int r = 8; r < 16; ++r) mx = fmaxf(mx, n1[r]);
;   pm = mx;
; }
	v_mfma_f32_32x32x16_f16 v[66:81], v[114:117], v[130:133], v[66:81]
	v_exp_f32_e32 v200, v99
	v_sub_f32_e32 v99, v105, v191
	v_add_f32_e32 v98, v197, v98
	v_exp_f32_e32 v201, v99
	v_sub_f32_e32 v99, v106, v191
	v_add_f32_e32 v98, v198, v98
	v_add_f32_e32 v98, v199, v98
	v_mfma_f32_32x32x16_f16 v[82:97], v[118:121], v[130:133], v[82:97]
	v_exp_f32_e32 v118, v99
	v_sub_f32_e32 v99, v107, v191
	v_exp_f32_e32 v119, v99
	v_sub_f32_e32 v99, v108, v191
	v_add_f32_e32 v98, v200, v98
	v_exp_f32_e32 v120, v99
	v_sub_f32_e32 v99, v109, v191
	v_add_f32_e32 v98, v201, v98
	v_exp_f32_e32 v121, v99
	v_sub_f32_e32 v99, v110, v191
	v_mfma_f32_32x32x16_f16 v[66:81], v[122:125], v[134:137], v[66:81]
	v_add_f32_e32 v98, v118, v98
	v_exp_f32_e32 v122, v99
	v_sub_f32_e32 v99, v111, v191
	v_add_f32_e32 v98, v119, v98
	v_exp_f32_e32 v123, v99
	v_sub_f32_e32 v99, v112, v191
	v_add_f32_e32 v98, v120, v98
	v_exp_f32_e32 v124, v99
	v_sub_f32_e32 v99, v113, v191
	v_add_f32_e32 v98, v121, v98
	v_exp_f32_e32 v125, v99
	v_add_f32_e32 v98, v122, v98
	v_add_f32_e32 v98, v123, v98
	v_add_f32_e32 v98, v124, v98
	v_add_f32_e32 v98, v125, v98
	v_add_f32_e32 v193, v193, v98
	ds_read_b64_tr_b16 v[98:99], v212 offset:0
	ds_read_b64_tr_b16 v[100:101], v213 offset:0x800
	ds_read_b64_tr_b16 v[102:103], v212 offset:0x1000
	v_mfma_f32_32x32x16_f16 v[82:97], v[126:129], v[134:137], v[82:97]
	ds_read_b64_tr_b16 v[104:105], v213 offset:0x1800
	ds_read_b64_tr_b16 v[106:107], v212 offset:0x2000
	ds_read_b64_tr_b16 v[108:109], v213 offset:0x2800
	ds_read_b64_tr_b16 v[110:111], v212 offset:0x3000
	ds_read_b64_tr_b16 v[112:113], v213 offset:0x3800
	s_waitcnt lgkmcnt(0)
	v_cvt_pk_f16_f32 v117, v220, v221
	v_cvt_pk_f16_f32 v116, v218, v219
	v_cvt_pk_f16_f32 v115, v216, v217
	v_cvt_pk_f16_f32 v114, v214, v215
	s_nop 1
	v_mfma_f32_32x32x16_f16 v[50:65], v[98:101], v[114:117], v[50:65]
	v_cvt_pk_f16_f32 v101, v210, v211
	v_cvt_pk_f16_f32 v100, v208, v209
	v_cvt_pk_f16_f32 v99, v204, v205
	v_cvt_pk_f16_f32 v98, v202, v203
	s_nop 1
	v_mfma_f32_32x32x16_f16 v[50:65], v[102:105], v[98:101], v[50:65]
	v_cvt_pk_f16_f32 v105, v200, v201
	v_cvt_pk_f16_f32 v104, v198, v199
	v_cvt_pk_f16_f32 v103, v196, v197
	v_cvt_pk_f16_f32 v102, v194, v195
	v_max_f32_e32 v194, v67, v67
	v_max_f32_e32 v195, v66, v66
	v_max_f32_e32 v194, v195, v194
	v_mfma_f32_32x32x16_f16 v[50:65], v[106:109], v[102:105], v[50:65]
	v_cvt_pk_f16_f32 v109, v124, v125
	v_cvt_pk_f16_f32 v108, v122, v123
	v_cvt_pk_f16_f32 v107, v120, v121
	v_cvt_pk_f16_f32 v106, v118, v119
	v_max3_f32 v194, v194, v68, v69
	v_max3_f32 v194, v194, v70, v71
	v_max3_f32 v194, v194, v72, v73
	v_mfma_f32_32x32x16_f16 v[50:65], v[110:113], v[106:109], v[50:65]
	ds_read_b64_tr_b16 v[110:111], v212 offset:0x200
	ds_read_b64_tr_b16 v[112:113], v213 offset:0xa00
	ds_read_b64_tr_b16 v[118:119], v212 offset:0x1200
	ds_read_b64_tr_b16 v[120:121], v213 offset:0x1a00
	ds_read_b64_tr_b16 v[122:123], v212 offset:0x2200
	ds_read_b64_tr_b16 v[124:125], v213 offset:0x2a00
	ds_read_b64_tr_b16 v[126:127], v212 offset:0x3200
	ds_read_b64_tr_b16 v[128:129], v213 offset:0x3a00
	s_waitcnt lgkmcnt(0)
	s_nop 0
	v_mfma_f32_32x32x16_f16 v[34:49], v[110:113], v[114:117], v[34:49]
	ds_read_b64_tr_b16 v[110:111], v212 offset:0x400
	ds_read_b64_tr_b16 v[112:113], v213 offset:0xc00
	v_max3_f32 v194, v194, v74, v75
	v_max3_f32 v194, v194, v76, v77
	v_max3_f32 v194, v194, v78, v79
	v_max3_f32 v194, v194, v80, v81
	v_mfma_f32_32x32x16_f16 v[34:49], v[118:121], v[98:101], v[34:49]
	ds_read_b64_tr_b16 v[118:119], v212 offset:0x1400
	ds_read_b64_tr_b16 v[120:121], v213 offset:0x1c00
	v_mfma_f32_32x32x16_f16 v[34:49], v[122:125], v[102:105], v[34:49]
	ds_read_b64_tr_b16 v[122:123], v212 offset:0x2400
	ds_read_b64_tr_b16 v[124:125], v213 offset:0x2c00
	v_mfma_f32_32x32x16_f16 v[34:49], v[126:129], v[106:109], v[34:49]
	ds_read_b64_tr_b16 v[126:127], v212 offset:0x3400
	ds_read_b64_tr_b16 v[128:129], v213 offset:0x3c00
	s_waitcnt lgkmcnt(0)
	v_mfma_f32_32x32x16_f16 v[18:33], v[110:113], v[114:117], v[18:33]
	ds_read_b64_tr_b16 v[110:111], v212 offset:0x600
	ds_read_b64_tr_b16 v[112:113], v213 offset:0xe00
	v_max3_f32 v194, v194, v82, v83
	v_max3_f32 v194, v194, v84, v85
	v_max3_f32 v194, v194, v86, v87
	v_max3_f32 v194, v194, v88, v89
	v_mfma_f32_32x32x16_f16 v[18:33], v[118:121], v[98:101], v[18:33]
	ds_read_b64_tr_b16 v[118:119], v212 offset:0x1600
	ds_read_b64_tr_b16 v[120:121], v213 offset:0x1e00
	v_mfma_f32_32x32x16_f16 v[18:33], v[122:125], v[102:105], v[18:33]
	ds_read_b64_tr_b16 v[122:123], v212 offset:0x2600
	ds_read_b64_tr_b16 v[124:125], v213 offset:0x2e00
	v_mfma_f32_32x32x16_f16 v[18:33], v[126:129], v[106:109], v[18:33]
	ds_read_b64_tr_b16 v[126:127], v212 offset:0x3600
	ds_read_b64_tr_b16 v[128:129], v213 offset:0x3e00
	s_waitcnt lgkmcnt(0)
	v_mfma_f32_32x32x16_f16 v[2:17], v[110:113], v[114:117], v[2:17]
	v_mfma_f32_32x32x16_f16 v[2:17], v[118:121], v[98:101], v[2:17]
	v_max3_f32 v98, v194, v90, v91
	v_max3_f32 v98, v98, v92, v93
	v_max3_f32 v98, v98, v94, v95
	v_max3_f32 v98, v98, v96, v97
	v_mov_b32_e32 v99, v98
	s_nop 1
	v_permlane32_swap_b32_e32 v98, v99
	v_mfma_f32_32x32x16_f16 v[2:17], v[122:125], v[102:105], v[2:17]
	v_max_f32_e32 v99, v99, v99
	v_max_f32_e32 v98, v98, v98
	v_max_f32_e32 v98, v98, v99
	v_sub_f32_e32 v99, v98, v191
	v_cmp_ge_f32_e32 vcc, s73, v99
	s_cmp_eq_u64 vcc, exec
	v_mfma_f32_32x32x16_f16 v[2:17], v[126:129], v[106:109], v[2:17]
	s_cbranch_scc1 .LBB0_694
; DI float fexp2(float x) { return __builtin_amdgcn_exp2f(x); }
; #define VWAIT(n) asm volatile("s_waitcnt vmcnt(" #n ")" ::: "memory")
; DI void osm_decide(float pmn, float& m, float& l, f32x16 (&o)[4]) {
;   if (!__all(pmn - m <= THR)) {
;     float mn = fmaxf(m, pmn); float alpha = fexp2(m - mn); m = mn; l *= alpha;
; #pragma unroll
;     for (int d = 0; d < 4; ++d)
; #pragma unroll
;       for (int r = 0; r < 16; ++r) o[d][r] *= alpha;
;   }
; }
; DI void ring_wait4(int rem) {
;   if (rem >= 3) VWAIT(12); else if (rem == 2) VWAIT(8); else if (rem == 1) VWAIT(4); else VWAIT(0);
; }
	v_max_f32_e32 v98, v98, v98
	v_max_f32_e32 v99, v191, v191
	v_max_f32_e32 v99, v99, v98
	v_sub_f32_e32 v98, v191, v99
	v_exp_f32_e32 v98, v98
	v_mov_b32_e32 v191, v99
	v_mul_f32_e32 v193, v193, v98
	v_pk_mul_f32 v[64:65], v[64:65], v[98:99] op_sel_hi:[1,0]
	v_pk_mul_f32 v[62:63], v[62:63], v[98:99] op_sel_hi:[1,0]
	v_pk_mul_f32 v[60:61], v[60:61], v[98:99] op_sel_hi:[1,0]
	v_pk_mul_f32 v[58:59], v[58:59], v[98:99] op_sel_hi:[1,0]
	v_pk_mul_f32 v[56:57], v[56:57], v[98:99] op_sel_hi:[1,0]
	v_pk_mul_f32 v[54:55], v[54:55], v[98:99] op_sel_hi:[1,0]
	v_pk_mul_f32 v[52:53], v[52:53], v[98:99] op_sel_hi:[1,0]
	v_pk_mul_f32 v[50:51], v[50:51], v[98:99] op_sel_hi:[1,0]
	v_pk_mul_f32 v[48:49], v[48:49], v[98:99] op_sel_hi:[1,0]
	v_pk_mul_f32 v[46:47], v[46:47], v[98:99] op_sel_hi:[1,0]
	v_pk_mul_f32 v[44:45], v[44:45], v[98:99] op_sel_hi:[1,0]
	v_pk_mul_f32 v[42:43], v[42:43], v[98:99] op_sel_hi:[1,0]
	v_pk_mul_f32 v[40:41], v[40:41], v[98:99] op_sel_hi:[1,0]
	v_pk_mul_f32 v[38:39], v[38:39], v[98:99] op_sel_hi:[1,0]
	v_pk_mul_f32 v[36:37], v[36:37], v[98:99] op_sel_hi:[1,0]
	v_pk_mul_f32 v[34:35], v[34:35], v[98:99] op_sel_hi:[1,0]
	v_pk_mul_f32 v[32:33], v[32:33], v[98:99] op_sel_hi:[1,0]
	v_pk_mul_f32 v[30:31], v[30:31], v[98:99] op_sel_hi:[1,0]
	v_pk_mul_f32 v[28:29], v[28:29], v[98:99] op_sel_hi:[1,0]
	v_pk_mul_f32 v[26:27], v[26:27], v[98:99] op_sel_hi:[1,0]
	v_pk_mul_f32 v[24:25], v[24:25], v[98:99] op_sel_hi:[1,0]
	v_pk_mul_f32 v[22:23], v[22:23], v[98:99] op_sel_hi:[1,0]
	v_pk_mul_f32 v[20:21], v[20:21], v[98:99] op_sel_hi:[1,0]
	v_pk_mul_f32 v[18:19], v[18:19], v[98:99] op_sel_hi:[1,0]
	v_pk_mul_f32 v[16:17], v[16:17], v[98:99] op_sel_hi:[1,0]
	v_pk_mul_f32 v[14:15], v[14:15], v[98:99] op_sel_hi:[1,0]
	v_pk_mul_f32 v[12:13], v[12:13], v[98:99] op_sel_hi:[1,0]
	v_pk_mul_f32 v[10:11], v[10:11], v[98:99] op_sel_hi:[1,0]
	v_pk_mul_f32 v[8:9], v[8:9], v[98:99] op_sel_hi:[1,0]
	v_pk_mul_f32 v[6:7], v[6:7], v[98:99] op_sel_hi:[1,0]
	v_pk_mul_f32 v[4:5], v[4:5], v[98:99] op_sel_hi:[1,0]
	v_pk_mul_f32 v[2:3], v[2:3], v[98:99] op_sel_hi:[1,0]
	s_branch .LBB0_694
.Lvm_slow3:
	s_add_i32 s0, s6, -2
	s_cmp_lt_i32 s0, 3
	s_mov_b64 s[0:1], -1
	s_cbranch_scc0 .LBB0_756
	s_cmp_gt_i32 s6, 3
	s_cbranch_scc0 .LBB0_750
	s_waitcnt vmcnt(8)
	s_mov_b64 s[0:1], 0

; #define VWAIT(n) asm volatile("s_waitcnt vmcnt(" #n ")" ::: "memory")
; #define WIN_STEP(C0, C1, X0, X1) do { \
;       NSA_STEP(n + 1); \
;       float ps, pmn; \
;       qk_exp(X0, X1, smem + ((n + 1) & 3) * 32768, qf, kbe, kbo, C0, C1, m, ps); \
;       l += ps; \
;       pv_max(o, vr0 + (n & 3) * 32768, vr1 + (n & 3) * 32768, C0, C1, X0, X1, pmn); \
;       pmn = xhalf_max(pmn); \
;       osm_decide(pmn, m, l, o); } while (0)
; DI void ring_wait4(int rem) {
;   if (rem >= 3) VWAIT(12); else if (rem == 2) VWAIT(8); else if (rem == 1) VWAIT(4); else VWAIT(0);
; }
; DI void nsa_unit(const Params& p, int b, int g, int qt, char* smem) {
;     ...
;     if (n < nb) { WIN_STEP(c0, c1, x0, x1); c0 = x0; c1 = x1; }
.LBB0_746:
	s_cmp_ge_i32 s5, s4
	s_cbranch_scc1 .LBB0_769
	s_sub_i32 s6, s18, s5
	s_cmp_lg_u32 s6, 3
	s_cbranch_scc1 .Lvm_slow3
	s_waitcnt vmcnt(4)
